# O9S + s_setprio 3 around the P4 forward-substitution solver wave (its SIMD partner runs the conv branch)
# speedup vs baseline: 1.0019x; 1.0019x over previous
.LBB0_557:
	s_and_b64 vcc, exec, s[16:17]
	s_cbranch_vccz .LBB0_498
	s_setprio 3
	v_mov_b32_e32 v6, v125
	s_nop 0
	v_lshl_add_u32 v11, v6, 2, s85
	ds_read_b128 v[12:15], v11 offset:52224
	ds_read_b128 v[16:19], v11 offset:52240
	ds_read_b128 v[20:23], v11 offset:52256
	ds_read_b128 v[24:27], v11 offset:52272
	v_add_u32_e32 v7, 0xcc00, v11
	ds_read_b128 v[28:31], v11 offset:52288
	ds_read_b128 v[32:35], v11 offset:52304
	ds_read_b128 v[36:39], v11 offset:52320
	ds_read_b128 v[40:43], v11 offset:52336
	ds_read_b128 v[44:47], v11 offset:52352
	ds_read_b128 v[48:51], v11 offset:52368
	ds_read_b128 v[52:55], v11 offset:52384
	ds_read_b128 v[56:59], v11 offset:52400
	ds_read_b128 v[60:63], v11 offset:52416
	ds_read_b128 v[64:67], v11 offset:52432
	ds_read_b128 v[68:71], v11 offset:52448
	ds_read_b128 v[72:75], v11 offset:52464
	s_waitcnt lgkmcnt(14)
	v_fma_f32 v6, -v158, v13, v159
	v_fma_f32 v8, -v158, v14, v160
	v_fma_f32 v9, -v158, v15, v161
	v_fma_f32 v10, -v158, v16, v162
	v_fma_f32 v80, -v158, v17, v163
	v_fma_f32 v81, -v158, v18, v164
	v_fma_f32 v82, -v158, v19, v165
	s_waitcnt lgkmcnt(13)
	v_fma_f32 v83, -v158, v20, v166
	v_fma_f32 v84, -v158, v21, v167
	v_fma_f32 v85, -v158, v22, v168
	v_fma_f32 v86, -v158, v23, v169
	ds_read_b128 v[12:15], v11 offset:52496
	ds_read_b128 v[16:19], v11 offset:52512
	ds_read_b128 v[20:23], v11 offset:52528
	ds_read_b128 v[76:79], v11 offset:52544
	s_waitcnt lgkmcnt(14)
	v_fma_f32 v87, -v158, v24, v170
	v_fma_f32 v88, -v158, v25, v171
	v_fma_f32 v89, -v158, v26, v172
	v_fma_f32 v90, -v158, v27, v173
	v_fma_f32 v91, -v158, v28, v174
	v_fma_f32 v92, -v158, v29, v175
	v_fma_f32 v93, -v158, v30, v176
	v_fma_f32 v94, -v158, v31, v177
	v_fma_f32 v95, -v158, v32, v178
	v_fma_f32 v96, -v158, v33, v179
	v_fma_f32 v97, -v158, v34, v180
	v_fma_f32 v98, -v158, v35, v181
	s_waitcnt lgkmcnt(13)
	v_fma_f32 v99, -v158, v36, v182
	v_fma_f32 v100, -v158, v37, v183
	v_fma_f32 v101, -v158, v38, v184
	v_fma_f32 v102, -v158, v39, v185
	ds_read_b128 v[24:27], v11 offset:52560
	ds_read_b128 v[28:31], v11 offset:52576
	ds_read_b128 v[32:35], v11 offset:52592
	ds_read_b128 v[36:39], v11 offset:52608
	s_waitcnt lgkmcnt(14)
	v_fma_f32 v103, -v158, v40, v186
	v_fma_f32 v104, -v158, v41, v187
	v_fma_f32 v105, -v158, v42, v188
	v_fma_f32 v106, -v158, v43, v189
	v_fma_f32 v107, -v158, v44, v190
	v_fma_f32 v108, -v158, v45, v191
	v_fma_f32 v109, -v158, v46, v192
	v_fma_f32 v110, -v158, v47, v193
	v_fma_f32 v111, -v158, v48, v194
	v_fma_f32 v112, -v158, v49, v195
	v_fma_f32 v113, -v158, v50, v196
	v_fma_f32 v114, -v158, v51, v197
	s_waitcnt lgkmcnt(13)
	v_fma_f32 v115, -v158, v52, v198
	v_fma_f32 v116, -v158, v53, v199
	v_fma_f32 v117, -v158, v54, v200
	v_fma_f32 v118, -v158, v55, v201
	ds_read_b128 v[40:43], v11 offset:52624
	ds_read_b128 v[44:47], v11 offset:52640
	ds_read_b128 v[48:51], v11 offset:52656
	ds_read_b128 v[52:55], v11 offset:52672
	s_waitcnt lgkmcnt(14)
	v_fma_f32 v119, -v158, v56, v202
	v_fma_f32 v120, -v158, v57, v203
	v_fma_f32 v121, -v158, v58, v204
	v_fma_f32 v124, -v158, v59, v205
	v_fma_f32 v129, -v158, v60, v206
	v_fma_f32 v130, -v158, v61, v207
	v_fma_f32 v131, -v158, v62, v208
	v_fma_f32 v132, -v158, v63, v209
	v_fma_f32 v133, -v158, v64, v210
	v_fma_f32 v134, -v158, v65, v211
	v_fma_f32 v135, -v158, v66, v212
	v_fma_f32 v136, -v158, v67, v213
	s_waitcnt lgkmcnt(13)
	v_fma_f32 v137, -v158, v68, v214
	v_fma_f32 v138, -v158, v69, v215
	v_fma_f32 v139, -v158, v70, v216
	v_fma_f32 v140, -v158, v71, v217
	ds_read_b128 v[56:59], v11 offset:52688
	ds_read_b128 v[60:63], v11 offset:52704
	ds_read_b128 v[64:67], v11 offset:52720
	ds_read_b128 v[68:71], v11 offset:52736
	s_waitcnt lgkmcnt(14)
	v_fma_f32 v141, -v158, v72, v218
	v_fma_f32 v142, -v158, v73, v219
	v_fma_f32 v143, -v158, v74, v220
	v_fma_f32 v144, -v158, v75, v221
	v_fma_f32 v8, -v6, v14, v8
	v_fma_f32 v9, -v6, v15, v9
	v_fma_f32 v10, -v6, v16, v10
	v_fma_f32 v80, -v6, v17, v80
	v_fma_f32 v81, -v6, v18, v81
	v_fma_f32 v82, -v6, v19, v82
	s_waitcnt lgkmcnt(13)
	v_fma_f32 v83, -v6, v20, v83
	v_fma_f32 v84, -v6, v21, v84
	v_fma_f32 v85, -v6, v22, v85
	v_fma_f32 v86, -v6, v23, v86
	ds_read_b128 v[12:15], v11 offset:52768
	ds_read_b128 v[16:19], v11 offset:52784
	ds_read_b128 v[20:23], v11 offset:52800
	ds_read_b128 v[72:75], v11 offset:52816
	s_waitcnt lgkmcnt(14)
	v_fma_f32 v87, -v6, v76, v87
	v_fma_f32 v88, -v6, v77, v88
	v_fma_f32 v89, -v6, v78, v89
	v_fma_f32 v90, -v6, v79, v90
	v_fma_f32 v91, -v6, v24, v91
	v_fma_f32 v92, -v6, v25, v92
	v_fma_f32 v93, -v6, v26, v93
	v_fma_f32 v94, -v6, v27, v94
	v_fma_f32 v95, -v6, v28, v95
	v_fma_f32 v96, -v6, v29, v96
	v_fma_f32 v97, -v6, v30, v97
	v_fma_f32 v98, -v6, v31, v98
	s_waitcnt lgkmcnt(13)
	v_fma_f32 v99, -v6, v32, v99
	v_fma_f32 v100, -v6, v33, v100
	v_fma_f32 v101, -v6, v34, v101
	v_fma_f32 v102, -v6, v35, v102
	ds_read_b128 v[24:27], v11 offset:52832
	ds_read_b128 v[28:31], v11 offset:52848
	ds_read_b128 v[32:35], v11 offset:52864
	ds_read_b128 v[76:79], v11 offset:52880
	s_waitcnt lgkmcnt(14)
	v_fma_f32 v103, -v6, v36, v103
	v_fma_f32 v104, -v6, v37, v104
	v_fma_f32 v105, -v6, v38, v105
	v_fma_f32 v106, -v6, v39, v106
	v_fma_f32 v107, -v6, v40, v107
	v_fma_f32 v108, -v6, v41, v108
	v_fma_f32 v109, -v6, v42, v109
	v_fma_f32 v110, -v6, v43, v110
	v_fma_f32 v111, -v6, v44, v111
	v_fma_f32 v112, -v6, v45, v112
	v_fma_f32 v113, -v6, v46, v113
	v_fma_f32 v114, -v6, v47, v114
	s_waitcnt lgkmcnt(13)
	v_fma_f32 v115, -v6, v48, v115
	v_fma_f32 v116, -v6, v49, v116
	v_fma_f32 v117, -v6, v50, v117
	v_fma_f32 v118, -v6, v51, v118
	ds_read_b128 v[36:39], v11 offset:52896
	ds_read_b128 v[40:43], v11 offset:52912
	ds_read_b128 v[44:47], v11 offset:52928
	ds_read_b128 v[48:51], v11 offset:52944
	s_waitcnt lgkmcnt(14)
	v_fma_f32 v119, -v6, v52, v119
	v_fma_f32 v120, -v6, v53, v120
	v_fma_f32 v121, -v6, v54, v121
	v_fma_f32 v124, -v6, v55, v124
	v_fma_f32 v129, -v6, v56, v129
	v_fma_f32 v130, -v6, v57, v130
	v_fma_f32 v131, -v6, v58, v131
	v_fma_f32 v132, -v6, v59, v132
	v_fma_f32 v133, -v6, v60, v133
	v_fma_f32 v134, -v6, v61, v134
	v_fma_f32 v135, -v6, v62, v135
	v_fma_f32 v136, -v6, v63, v136
	s_waitcnt lgkmcnt(13)
	v_fma_f32 v137, -v6, v64, v137
	v_fma_f32 v138, -v6, v65, v138
	v_fma_f32 v139, -v6, v66, v139
	v_fma_f32 v140, -v6, v67, v140
	ds_read_b128 v[52:55], v11 offset:52960
	ds_read_b128 v[56:59], v11 offset:52976
	ds_read_b128 v[60:63], v11 offset:52992
	ds_read_b128 v[64:67], v11 offset:53008
	s_waitcnt lgkmcnt(14)
	v_fma_f32 v141, -v6, v68, v141
	v_fma_f32 v142, -v6, v69, v142
	v_fma_f32 v143, -v6, v70, v143
	v_fma_f32 v144, -v6, v71, v144
	v_fma_f32 v9, -v8, v15, v9
	v_fma_f32 v10, -v8, v16, v10
	v_fma_f32 v80, -v8, v17, v80
	v_fma_f32 v81, -v8, v18, v81
	v_fma_f32 v82, -v8, v19, v82
	s_waitcnt lgkmcnt(13)
	v_fma_f32 v83, -v8, v20, v83
	v_fma_f32 v84, -v8, v21, v84
	v_fma_f32 v85, -v8, v22, v85
	v_fma_f32 v86, -v8, v23, v86
	ds_read_b128 v[12:15], v11 offset:53056
	ds_read_b128 v[16:19], v11 offset:53072
	ds_read_b128 v[20:23], v11 offset:53088
	s_waitcnt lgkmcnt(14)
	v_fma_f32 v87, -v8, v72, v87
	v_fma_f32 v88, -v8, v73, v88
	v_fma_f32 v89, -v8, v74, v89
	v_fma_f32 v90, -v8, v75, v90
	v_fma_f32 v91, -v8, v24, v91
	v_fma_f32 v92, -v8, v25, v92
	v_fma_f32 v93, -v8, v26, v93
	v_fma_f32 v94, -v8, v27, v94
	s_waitcnt lgkmcnt(13)
	v_fma_f32 v95, -v8, v28, v95
	v_fma_f32 v96, -v8, v29, v96
	v_fma_f32 v97, -v8, v30, v97
	v_fma_f32 v98, -v8, v31, v98
	s_waitcnt lgkmcnt(12)
	v_fma_f32 v99, -v8, v32, v99
	v_fma_f32 v100, -v8, v33, v100
	v_fma_f32 v101, -v8, v34, v101
	v_fma_f32 v102, -v8, v35, v102
	ds_read_b128 v[24:27], v11 offset:53104
	ds_read_b128 v[28:31], v11 offset:53120
	ds_read_b128 v[32:35], v11 offset:53136
	ds_read_b128 v[68:71], v11 offset:53152
	s_waitcnt lgkmcnt(14)
	v_fma_f32 v76, -v8, v76, v103
	v_fma_f32 v77, -v8, v77, v104
	v_fma_f32 v78, -v8, v78, v105
	v_fma_f32 v79, -v8, v79, v106
	v_fma_f32 v103, -v8, v36, v107
	v_fma_f32 v104, -v8, v37, v108
	v_fma_f32 v105, -v8, v38, v109
	v_fma_f32 v106, -v8, v39, v110
	s_waitcnt lgkmcnt(13)
	v_fma_f32 v107, -v8, v40, v111
	v_fma_f32 v108, -v8, v41, v112
	v_fma_f32 v109, -v8, v42, v113
	v_fma_f32 v110, -v8, v43, v114
	s_waitcnt lgkmcnt(12)
	v_fma_f32 v111, -v8, v44, v115
	v_fma_f32 v112, -v8, v45, v116
	v_fma_f32 v113, -v8, v46, v117
	v_fma_f32 v114, -v8, v47, v118
	ds_read_b128 v[36:39], v11 offset:53168
	ds_read_b128 v[40:43], v11 offset:53184
	ds_read_b128 v[44:47], v11 offset:53200
	ds_read_b128 v[72:75], v11 offset:53216
	s_waitcnt lgkmcnt(14)
	v_fma_f32 v115, -v8, v48, v119
	v_fma_f32 v116, -v8, v49, v120
	v_fma_f32 v117, -v8, v50, v121
	v_fma_f32 v118, -v8, v51, v124
	v_fma_f32 v119, -v8, v52, v129
	v_fma_f32 v120, -v8, v53, v130
	v_fma_f32 v121, -v8, v54, v131
	v_fma_f32 v124, -v8, v55, v132
	s_waitcnt lgkmcnt(13)
	v_fma_f32 v129, -v8, v56, v133
	v_fma_f32 v130, -v8, v57, v134
	v_fma_f32 v131, -v8, v58, v135
	v_fma_f32 v132, -v8, v59, v136
	s_waitcnt lgkmcnt(12)
	v_fma_f32 v133, -v8, v60, v137
	v_fma_f32 v134, -v8, v61, v138
	v_fma_f32 v135, -v8, v62, v139
	v_fma_f32 v136, -v8, v63, v140
	ds_read_b128 v[48:51], v11 offset:53232
	ds_read_b128 v[52:55], v11 offset:53248
	ds_read_b128 v[56:59], v11 offset:53264
	ds_read_b128 v[60:63], v11 offset:53280
	s_waitcnt lgkmcnt(14)
	v_fma_f32 v137, -v8, v64, v141
	v_fma_f32 v138, -v8, v65, v142
	v_fma_f32 v139, -v8, v66, v143
	v_fma_f32 v140, -v8, v67, v144
	v_fma_f32 v10, -v9, v12, v10
	v_fma_f32 v80, -v9, v13, v80
	v_fma_f32 v81, -v9, v14, v81
	v_fma_f32 v82, -v9, v15, v82
	s_waitcnt lgkmcnt(13)
	v_fma_f32 v83, -v9, v16, v83
	v_fma_f32 v84, -v9, v17, v84
	v_fma_f32 v85, -v9, v18, v85
	v_fma_f32 v86, -v9, v19, v86
	ds_read_b128 v[12:15], v11 offset:53328
	ds_read_b128 v[16:19], v11 offset:53344
	ds_read_b128 v[64:67], v11 offset:53360
	s_waitcnt lgkmcnt(14)
	v_fma_f32 v87, -v9, v20, v87
	v_fma_f32 v88, -v9, v21, v88
	v_fma_f32 v89, -v9, v22, v89
	v_fma_f32 v90, -v9, v23, v90
	v_fma_f32 v91, -v9, v24, v91
	v_fma_f32 v92, -v9, v25, v92
	v_fma_f32 v93, -v9, v26, v93
	v_fma_f32 v94, -v9, v27, v94
	s_waitcnt lgkmcnt(13)
	v_fma_f32 v95, -v9, v28, v95
	v_fma_f32 v96, -v9, v29, v96
	v_fma_f32 v97, -v9, v30, v97
	v_fma_f32 v98, -v9, v31, v98
	s_waitcnt lgkmcnt(12)
	v_fma_f32 v99, -v9, v32, v99
	v_fma_f32 v100, -v9, v33, v100
	v_fma_f32 v101, -v9, v34, v101
	v_fma_f32 v102, -v9, v35, v102
	ds_read_b128 v[20:23], v11 offset:53376
	ds_read_b128 v[24:27], v11 offset:53392
	ds_read_b128 v[28:31], v11 offset:53408
	ds_read_b128 v[32:35], v11 offset:53424
	s_waitcnt lgkmcnt(14)
	v_fma_f32 v141, -v9, v68, v76
	v_fma_f32 v142, -v9, v69, v77
	v_fma_f32 v143, -v9, v70, v78
	v_fma_f32 v144, -v9, v71, v79
	v_fma_f32 v103, -v9, v36, v103
	v_fma_f32 v104, -v9, v37, v104
	v_fma_f32 v105, -v9, v38, v105
	v_fma_f32 v106, -v9, v39, v106
	s_waitcnt lgkmcnt(13)
	v_fma_f32 v107, -v9, v40, v107
	v_fma_f32 v108, -v9, v41, v108
	v_fma_f32 v109, -v9, v42, v109
	v_fma_f32 v110, -v9, v43, v110
	s_waitcnt lgkmcnt(12)
	v_fma_f32 v111, -v9, v44, v111
	v_fma_f32 v112, -v9, v45, v112
	v_fma_f32 v113, -v9, v46, v113
	v_fma_f32 v114, -v9, v47, v114
	ds_read_b128 v[36:39], v11 offset:53440
	ds_read_b128 v[40:43], v11 offset:53456
	ds_read_b128 v[44:47], v11 offset:53472
	ds_read_b128 v[68:71], v11 offset:53488
	s_waitcnt lgkmcnt(14)
	v_fma_f32 v115, -v9, v72, v115
	v_fma_f32 v116, -v9, v73, v116
	v_fma_f32 v117, -v9, v74, v117
	v_fma_f32 v118, -v9, v75, v118
	v_fma_f32 v119, -v9, v48, v119
	v_fma_f32 v120, -v9, v49, v120
	v_fma_f32 v121, -v9, v50, v121
	v_fma_f32 v124, -v9, v51, v124
	s_waitcnt lgkmcnt(13)
	v_fma_f32 v129, -v9, v52, v129
	v_fma_f32 v130, -v9, v53, v130
	v_fma_f32 v131, -v9, v54, v131
	v_fma_f32 v132, -v9, v55, v132
	s_waitcnt lgkmcnt(12)
	v_fma_f32 v133, -v9, v56, v133
	v_fma_f32 v134, -v9, v57, v134
	v_fma_f32 v135, -v9, v58, v135
	v_fma_f32 v136, -v9, v59, v136
	ds_read_b128 v[48:51], v11 offset:53504
	ds_read_b128 v[52:55], v11 offset:53520
	ds_read_b128 v[56:59], v11 offset:53536
	ds_read_b128 v[72:75], v11 offset:53552
	s_waitcnt lgkmcnt(14)
	v_fma_f32 v137, -v9, v60, v137
	v_fma_f32 v138, -v9, v61, v138
	v_fma_f32 v139, -v9, v62, v139
	v_fma_f32 v140, -v9, v63, v140
	v_fma_f32 v12, -v10, v13, v80
	v_fma_f32 v13, -v10, v14, v81
	v_fma_f32 v80, -v10, v15, v82
	s_waitcnt lgkmcnt(13)
	v_fma_f32 v81, -v10, v16, v83
	v_fma_f32 v82, -v10, v17, v84
	ds_read_b128 v[14:17], v11 offset:53600
	ds_read_b128 v[60:63], v11 offset:53616
	ds_read_b128 v[76:79], v11 offset:53632
	v_fma_f32 v83, -v10, v18, v85
	v_fma_f32 v84, -v10, v19, v86
	s_waitcnt lgkmcnt(14)
	v_fma_f32 v85, -v10, v64, v87
	v_fma_f32 v86, -v10, v65, v88
	v_fma_f32 v87, -v10, v66, v89
	v_fma_f32 v88, -v10, v67, v90
	v_fma_f32 v89, -v10, v20, v91
	v_fma_f32 v90, -v10, v21, v92
	v_fma_f32 v91, -v10, v22, v93
	v_fma_f32 v92, -v10, v23, v94
	s_waitcnt lgkmcnt(13)
	v_fma_f32 v93, -v10, v24, v95
	v_fma_f32 v94, -v10, v25, v96
	v_fma_f32 v95, -v10, v26, v97
	v_fma_f32 v96, -v10, v27, v98
	s_waitcnt lgkmcnt(12)
	v_fma_f32 v97, -v10, v28, v99
	v_fma_f32 v98, -v10, v29, v100
	ds_read_b128 v[18:21], v11 offset:53648
	ds_read_b128 v[22:25], v11 offset:53664
	ds_read_b128 v[26:29], v11 offset:53680
	ds_read_b128 v[64:67], v11 offset:53696
	v_fma_f32 v99, -v10, v30, v101
	v_fma_f32 v100, -v10, v31, v102
	s_waitcnt lgkmcnt(14)
	v_fma_f32 v101, -v10, v32, v141
	v_fma_f32 v102, -v10, v33, v142
	v_fma_f32 v141, -v10, v34, v143
	v_fma_f32 v142, -v10, v35, v144
	v_fma_f32 v103, -v10, v36, v103
	v_fma_f32 v104, -v10, v37, v104
	v_fma_f32 v105, -v10, v38, v105
	v_fma_f32 v106, -v10, v39, v106
	s_waitcnt lgkmcnt(13)
	v_fma_f32 v107, -v10, v40, v107
	v_fma_f32 v108, -v10, v41, v108
	v_fma_f32 v109, -v10, v42, v109
	v_fma_f32 v110, -v10, v43, v110
	s_waitcnt lgkmcnt(12)
	v_fma_f32 v111, -v10, v44, v111
	v_fma_f32 v112, -v10, v45, v112
	ds_read_b128 v[30:33], v11 offset:53712
	ds_read_b128 v[34:37], v11 offset:53728
	ds_read_b128 v[38:41], v11 offset:53744
	ds_read_b128 v[42:45], v11 offset:53760
	v_fma_f32 v113, -v10, v46, v113
	v_fma_f32 v114, -v10, v47, v114
	s_waitcnt lgkmcnt(14)
	v_fma_f32 v115, -v10, v68, v115
	v_fma_f32 v116, -v10, v69, v116
	v_fma_f32 v117, -v10, v70, v117
	v_fma_f32 v118, -v10, v71, v118
	v_fma_f32 v119, -v10, v48, v119
	v_fma_f32 v120, -v10, v49, v120
	v_fma_f32 v121, -v10, v50, v121
	v_fma_f32 v124, -v10, v51, v124
	s_waitcnt lgkmcnt(13)
	v_fma_f32 v129, -v10, v52, v129
	v_fma_f32 v130, -v10, v53, v130
	v_fma_f32 v131, -v10, v54, v131
	v_fma_f32 v132, -v10, v55, v132
	s_waitcnt lgkmcnt(12)
	v_fma_f32 v133, -v10, v56, v133
	v_fma_f32 v134, -v10, v57, v134
	ds_read_b128 v[46:49], v11 offset:53776
	ds_read_b128 v[50:53], v11 offset:53792
	ds_read_b128 v[54:57], v11 offset:53808
	ds_read_b128 v[68:71], v11 offset:53824
	v_fma_f32 v135, -v10, v58, v135
	v_fma_f32 v136, -v10, v59, v136
	s_waitcnt lgkmcnt(14)
	v_fma_f32 v137, -v10, v72, v137
	v_fma_f32 v138, -v10, v73, v138
	v_fma_f32 v139, -v10, v74, v139
	v_fma_f32 v140, -v10, v75, v140
	v_fma_f32 v13, -v12, v16, v13
	v_fma_f32 v80, -v12, v17, v80
	s_waitcnt lgkmcnt(13)
	v_fma_f32 v81, -v12, v60, v81
	v_fma_f32 v82, -v12, v61, v82
	ds_read_b128 v[14:17], v11 offset:53872
	ds_read_b128 v[58:61], v11 offset:53888
	ds_read_b128 v[72:75], v11 offset:53904
	v_fma_f32 v83, -v12, v62, v83
	v_fma_f32 v84, -v12, v63, v84
	s_waitcnt lgkmcnt(2)
	v_fma_f32 v15, -v12, v76, v85
	v_fma_f32 v16, -v12, v77, v86
	v_fma_f32 v85, -v12, v78, v87
	v_fma_f32 v86, -v12, v79, v88
	v_fma_f32 v87, -v12, v18, v89
	v_fma_f32 v88, -v12, v19, v90
	v_fma_f32 v89, -v12, v20, v91
	v_fma_f32 v90, -v12, v21, v92
	v_fma_f32 v91, -v12, v22, v93
	v_fma_f32 v92, -v12, v23, v94
	v_fma_f32 v93, -v12, v24, v95
	v_fma_f32 v94, -v12, v25, v96
	v_fma_f32 v95, -v12, v26, v97
	v_fma_f32 v96, -v12, v27, v98
	v_fma_f32 v97, -v12, v28, v99
	v_fma_f32 v98, -v12, v29, v100
	ds_read_b128 v[18:21], v11 offset:53920
	ds_read_b128 v[22:25], v11 offset:53936
	ds_read_b128 v[26:29], v11 offset:53952
	ds_read_b128 v[76:79], v11 offset:53968
	v_fma_f32 v99, -v12, v64, v101
	v_fma_f32 v100, -v12, v65, v102
	v_fma_f32 v101, -v12, v66, v141
	v_fma_f32 v102, -v12, v67, v142
	v_fma_f32 v103, -v12, v30, v103
	v_fma_f32 v104, -v12, v31, v104
	v_fma_f32 v105, -v12, v32, v105
	v_fma_f32 v106, -v12, v33, v106
	v_fma_f32 v107, -v12, v34, v107
	v_fma_f32 v108, -v12, v35, v108
	v_fma_f32 v109, -v12, v36, v109
	v_fma_f32 v110, -v12, v37, v110
	v_fma_f32 v111, -v12, v38, v111
	v_fma_f32 v112, -v12, v39, v112
	v_fma_f32 v113, -v12, v40, v113
	v_fma_f32 v114, -v12, v41, v114
	ds_read_b128 v[30:33], v11 offset:53984
	ds_read_b128 v[34:37], v11 offset:54000
	ds_read_b128 v[38:41], v11 offset:54016
	ds_read_b128 v[62:65], v11 offset:54032
	v_fma_f32 v115, -v12, v42, v115
	v_fma_f32 v116, -v12, v43, v116
	v_fma_f32 v117, -v12, v44, v117
	v_fma_f32 v118, -v12, v45, v118
	v_fma_f32 v119, -v12, v46, v119
	v_fma_f32 v120, -v12, v47, v120
	v_fma_f32 v121, -v12, v48, v121
	v_fma_f32 v124, -v12, v49, v124
	v_fma_f32 v129, -v12, v50, v129
	v_fma_f32 v130, -v12, v51, v130
	v_fma_f32 v131, -v12, v52, v131
	v_fma_f32 v132, -v12, v53, v132
	v_fma_f32 v133, -v12, v54, v133
	v_fma_f32 v134, -v12, v55, v134
	v_fma_f32 v135, -v12, v56, v135
	v_fma_f32 v136, -v12, v57, v136
	ds_read_b128 v[42:45], v11 offset:54048
	ds_read_b128 v[46:49], v11 offset:54064
	ds_read_b128 v[50:53], v11 offset:54080
	ds_read_b128 v[54:57], v11 offset:54096
	v_fma_f32 v137, -v12, v68, v137
	v_fma_f32 v138, -v12, v69, v138
	v_fma_f32 v139, -v12, v70, v139
	v_fma_f32 v140, -v12, v71, v140
	v_fma_f32 v14, -v13, v17, v80
	s_waitcnt lgkmcnt(13)
	v_fma_f32 v80, -v13, v58, v81
	v_fma_f32 v81, -v13, v59, v82
	v_fma_f32 v82, -v13, v60, v83
	v_fma_f32 v83, -v13, v61, v84
	ds_read_b128 v[58:61], v11 offset:54160
	ds_read_b128 v[66:69], v11 offset:54176
	s_waitcnt lgkmcnt(14)
	v_fma_f32 v84, -v13, v72, v15
	v_fma_f32 v141, -v13, v73, v16
	v_fma_f32 v85, -v13, v74, v85
	v_fma_f32 v86, -v13, v75, v86
	s_waitcnt lgkmcnt(13)
	v_fma_f32 v87, -v13, v18, v87
	v_fma_f32 v88, -v13, v19, v88
	v_fma_f32 v89, -v13, v20, v89
	v_fma_f32 v90, -v13, v21, v90
	s_waitcnt lgkmcnt(12)
	v_fma_f32 v91, -v13, v22, v91
	v_fma_f32 v92, -v13, v23, v92
	v_fma_f32 v93, -v13, v24, v93
	v_fma_f32 v94, -v13, v25, v94
	s_waitcnt lgkmcnt(11)
	v_fma_f32 v95, -v13, v26, v95
	v_fma_f32 v96, -v13, v27, v96
	ds_read_b128 v[16:19], v11 offset:54192
	ds_read_b128 v[20:23], v11 offset:54208
	ds_read_b128 v[24:27], v11 offset:54224
	ds_read_b128 v[70:73], v11 offset:54240
	v_fma_f32 v97, -v13, v28, v97
	v_fma_f32 v98, -v13, v29, v98
	s_waitcnt lgkmcnt(14)
	v_fma_f32 v99, -v13, v76, v99
	v_fma_f32 v100, -v13, v77, v100
	v_fma_f32 v101, -v13, v78, v101
	v_fma_f32 v102, -v13, v79, v102
	s_waitcnt lgkmcnt(13)
	v_fma_f32 v103, -v13, v30, v103
	v_fma_f32 v104, -v13, v31, v104
	v_fma_f32 v105, -v13, v32, v105
	v_fma_f32 v106, -v13, v33, v106
	s_waitcnt lgkmcnt(12)
	v_fma_f32 v107, -v13, v34, v107
	v_fma_f32 v108, -v13, v35, v108
	v_fma_f32 v109, -v13, v36, v109
	v_fma_f32 v110, -v13, v37, v110
	s_waitcnt lgkmcnt(11)
	v_fma_f32 v111, -v13, v38, v111
	v_fma_f32 v112, -v13, v39, v112
	ds_read_b128 v[28:31], v11 offset:54256
	ds_read_b128 v[32:35], v11 offset:54272
	ds_read_b128 v[36:39], v11 offset:54288
	ds_read_b128 v[74:77], v11 offset:54304
	v_fma_f32 v113, -v13, v40, v113
	v_fma_f32 v114, -v13, v41, v114
	s_waitcnt lgkmcnt(14)
	v_fma_f32 v115, -v13, v62, v115
	v_fma_f32 v116, -v13, v63, v116
	v_fma_f32 v117, -v13, v64, v117
	v_fma_f32 v118, -v13, v65, v118
	s_waitcnt lgkmcnt(13)
	v_fma_f32 v119, -v13, v42, v119
	v_fma_f32 v120, -v13, v43, v120
	v_fma_f32 v121, -v13, v44, v121
	v_fma_f32 v124, -v13, v45, v124
	s_waitcnt lgkmcnt(12)
	v_fma_f32 v129, -v13, v46, v129
	v_fma_f32 v130, -v13, v47, v130
	v_fma_f32 v131, -v13, v48, v131
	v_fma_f32 v132, -v13, v49, v132
	s_waitcnt lgkmcnt(11)
	v_fma_f32 v133, -v13, v50, v133
	v_fma_f32 v134, -v13, v51, v134
	ds_read_b128 v[40:43], v11 offset:54320
	ds_read_b128 v[44:47], v11 offset:54336
	ds_read_b128 v[48:51], v11 offset:54352
	ds_read_b128 v[62:65], v11 offset:54368
	v_fma_f32 v135, -v13, v52, v135
	v_fma_f32 v136, -v13, v53, v136
	s_waitcnt lgkmcnt(14)
	v_fma_f32 v137, -v13, v54, v137
	v_fma_f32 v138, -v13, v55, v138
	v_fma_f32 v139, -v13, v56, v139
	v_fma_f32 v140, -v13, v57, v140
	s_waitcnt lgkmcnt(13)
	v_fma_f32 v15, -v14, v58, v80
	v_fma_f32 v142, -v14, v59, v81
	ds_read_b128 v[52:55], v11 offset:54432
	ds_read_b128 v[56:59], v11 offset:54448
	v_fma_f32 v60, -v14, v60, v82
	v_fma_f32 v61, -v14, v61, v83
	s_waitcnt lgkmcnt(14)
	v_fma_f32 v82, -v14, v66, v84
	v_fma_f32 v83, -v14, v67, v141
	v_fma_f32 v84, -v14, v68, v85
	v_fma_f32 v85, -v14, v69, v86
	s_waitcnt lgkmcnt(13)
	v_fma_f32 v86, -v14, v16, v87
	v_fma_f32 v17, -v14, v17, v88
	v_fma_f32 v87, -v14, v18, v89
	v_fma_f32 v88, -v14, v19, v90
	s_waitcnt lgkmcnt(12)
	v_fma_f32 v89, -v14, v20, v91
	v_fma_f32 v90, -v14, v21, v92
	v_fma_f32 v91, -v14, v22, v93
	v_fma_f32 v92, -v14, v23, v94
	s_waitcnt lgkmcnt(11)
	v_fma_f32 v93, -v14, v24, v95
	v_fma_f32 v94, -v14, v25, v96
	ds_read_b128 v[18:21], v11 offset:54464
	ds_read_b128 v[22:25], v11 offset:54480
	ds_read_b128 v[66:69], v11 offset:54496
	ds_read_b128 v[78:81], v11 offset:54512
	v_fma_f32 v95, -v14, v26, v97
	v_fma_f32 v96, -v14, v27, v98
	s_waitcnt lgkmcnt(14)
	v_fma_f32 v97, -v14, v70, v99
	v_fma_f32 v98, -v14, v71, v100
	v_fma_f32 v99, -v14, v72, v101
	v_fma_f32 v100, -v14, v73, v102
	s_waitcnt lgkmcnt(13)
	v_fma_f32 v101, -v14, v28, v103
	v_fma_f32 v102, -v14, v29, v104
	v_fma_f32 v103, -v14, v30, v105
	v_fma_f32 v104, -v14, v31, v106
	s_waitcnt lgkmcnt(12)
	v_fma_f32 v105, -v14, v32, v107
	v_fma_f32 v106, -v14, v33, v108
	v_fma_f32 v107, -v14, v34, v109
	v_fma_f32 v108, -v14, v35, v110
	s_waitcnt lgkmcnt(11)
	v_fma_f32 v109, -v14, v36, v111
	v_fma_f32 v110, -v14, v37, v112
	ds_read_b128 v[26:29], v11 offset:54528
	ds_read_b128 v[30:33], v11 offset:54544
	ds_read_b128 v[34:37], v11 offset:54560
	ds_read_b128 v[70:73], v11 offset:54576
	v_fma_f32 v111, -v14, v38, v113
	v_fma_f32 v112, -v14, v39, v114
	s_waitcnt lgkmcnt(14)
	v_fma_f32 v113, -v14, v74, v115
	v_fma_f32 v114, -v14, v75, v116
	v_fma_f32 v115, -v14, v76, v117
	v_fma_f32 v116, -v14, v77, v118
	s_waitcnt lgkmcnt(13)
	v_fma_f32 v117, -v14, v40, v119
	v_fma_f32 v118, -v14, v41, v120
	v_fma_f32 v119, -v14, v42, v121
	v_fma_f32 v120, -v14, v43, v124
	s_waitcnt lgkmcnt(12)
	v_fma_f32 v121, -v14, v44, v129
	v_fma_f32 v124, -v14, v45, v130
	v_fma_f32 v129, -v14, v46, v131
	v_fma_f32 v130, -v14, v47, v132
	s_waitcnt lgkmcnt(11)
	v_fma_f32 v131, -v14, v48, v133
	v_fma_f32 v132, -v14, v49, v134
	ds_read_b128 v[38:41], v11 offset:54592
	ds_read_b128 v[42:45], v11 offset:54608
	ds_read_b128 v[46:49], v11 offset:54624
	ds_read_b128 v[74:77], v11 offset:54640
	v_fma_f32 v133, -v14, v50, v135
	v_fma_f32 v134, -v14, v51, v136
	s_waitcnt lgkmcnt(14)
	v_fma_f32 v135, -v14, v62, v137
	v_fma_f32 v136, -v14, v63, v138
	v_fma_f32 v137, -v14, v64, v139
	v_fma_f32 v138, -v14, v65, v140
	s_waitcnt lgkmcnt(13)
	v_fma_f32 v16, -v15, v53, v142
	v_fma_f32 v139, -v15, v54, v60
	v_fma_f32 v140, -v15, v55, v61
	ds_read_b128 v[50:53], v11 offset:54704
	ds_read_b128 v[60:63], v11 offset:54720
	s_waitcnt lgkmcnt(14)
	v_fma_f32 v82, -v15, v56, v82
	v_fma_f32 v83, -v15, v57, v83
	v_fma_f32 v58, -v15, v58, v84
	v_fma_f32 v59, -v15, v59, v85
	s_waitcnt lgkmcnt(13)
	v_fma_f32 v84, -v15, v18, v86
	v_fma_f32 v85, -v15, v19, v17
	v_fma_f32 v86, -v15, v20, v87
	v_fma_f32 v87, -v15, v21, v88
	s_waitcnt lgkmcnt(12)
	v_fma_f32 v88, -v15, v22, v89
	v_fma_f32 v89, -v15, v23, v90
	v_fma_f32 v90, -v15, v24, v91
	v_fma_f32 v91, -v15, v25, v92
	s_waitcnt lgkmcnt(11)
	v_fma_f32 v92, -v15, v66, v93
	v_fma_f32 v93, -v15, v67, v94
	ds_read_b128 v[18:21], v11 offset:54736
	ds_read_b128 v[22:25], v11 offset:54752
	ds_read_b128 v[54:57], v11 offset:54768
	ds_read_b128 v[64:67], v11 offset:54784
	v_fma_f32 v94, -v15, v68, v95
	v_fma_f32 v95, -v15, v69, v96
	s_waitcnt lgkmcnt(14)
	v_fma_f32 v96, -v15, v78, v97
	v_fma_f32 v97, -v15, v79, v98
	v_fma_f32 v98, -v15, v80, v99
	v_fma_f32 v99, -v15, v81, v100
	s_waitcnt lgkmcnt(13)
	v_fma_f32 v100, -v15, v26, v101
	v_fma_f32 v101, -v15, v27, v102
	v_fma_f32 v102, -v15, v28, v103
	v_fma_f32 v103, -v15, v29, v104
	s_waitcnt lgkmcnt(12)
	v_fma_f32 v104, -v15, v30, v105
	v_fma_f32 v105, -v15, v31, v106
	v_fma_f32 v106, -v15, v32, v107
	v_fma_f32 v107, -v15, v33, v108
	s_waitcnt lgkmcnt(11)
	v_fma_f32 v108, -v15, v34, v109
	v_fma_f32 v109, -v15, v35, v110
	v_fma_f32 v110, -v15, v36, v111
	v_fma_f32 v111, -v15, v37, v112
	ds_read_b128 v[26:29], v11 offset:54800
	ds_read_b128 v[30:33], v11 offset:54816
	ds_read_b128 v[34:37], v11 offset:54832
	ds_read_b128 v[78:81], v11 offset:54848
	s_waitcnt lgkmcnt(14)
	v_fma_f32 v112, -v15, v70, v113
	v_fma_f32 v113, -v15, v71, v114
	v_fma_f32 v114, -v15, v72, v115
	v_fma_f32 v115, -v15, v73, v116
	s_waitcnt lgkmcnt(13)
	v_fma_f32 v116, -v15, v38, v117
	v_fma_f32 v117, -v15, v39, v118
	v_fma_f32 v118, -v15, v40, v119
	v_fma_f32 v119, -v15, v41, v120
	s_waitcnt lgkmcnt(12)
	v_fma_f32 v120, -v15, v42, v121
	v_fma_f32 v121, -v15, v43, v124
	v_fma_f32 v124, -v15, v44, v129
	v_fma_f32 v129, -v15, v45, v130
	s_waitcnt lgkmcnt(11)
	v_fma_f32 v130, -v15, v46, v131
	v_fma_f32 v131, -v15, v47, v132
	v_fma_f32 v132, -v15, v48, v133
	v_fma_f32 v133, -v15, v49, v134
	ds_read_b128 v[38:41], v11 offset:54864
	ds_read_b128 v[42:45], v11 offset:54880
	ds_read_b128 v[46:49], v11 offset:54896
	ds_read_b128 v[68:71], v11 offset:54912
	s_waitcnt lgkmcnt(14)
	v_fma_f32 v134, -v15, v74, v135
	v_fma_f32 v135, -v15, v75, v136
	v_fma_f32 v76, -v15, v76, v137
	v_fma_f32 v77, -v15, v77, v138
	s_waitcnt lgkmcnt(13)
	v_fma_f32 v17, -v16, v52, v139
	v_fma_f32 v136, -v16, v53, v140
	ds_read_b128 v[50:53], v11 offset:54976
	ds_read_b128 v[72:75], v11 offset:54992
	s_waitcnt lgkmcnt(1)
	v_fma_f32 v52, -v16, v60, v82
	v_fma_f32 v137, -v16, v61, v83
	v_fma_f32 v138, -v16, v62, v58
	v_fma_f32 v139, -v16, v63, v59
	v_fma_f32 v140, -v16, v18, v84
	v_fma_f32 v19, -v16, v19, v85
	v_fma_f32 v86, -v16, v20, v86
	v_fma_f32 v87, -v16, v21, v87
	v_fma_f32 v88, -v16, v22, v88
	v_fma_f32 v89, -v16, v23, v89
	v_fma_f32 v92, -v16, v54, v92
	v_fma_f32 v93, -v16, v55, v93
	v_fma_f32 v94, -v16, v56, v94
	v_fma_f32 v95, -v16, v57, v95
	ds_read_b128 v[20:23], v11 offset:55008
	ds_read_b128 v[54:57], v11 offset:55024
	ds_read_b128 v[58:61], v11 offset:55040
	ds_read_b128 v[82:85], v11 offset:55056
	v_fma_f32 v90, -v16, v24, v90
	v_fma_f32 v91, -v16, v25, v91
	v_fma_f32 v96, -v16, v64, v96
	v_fma_f32 v97, -v16, v65, v97
	v_fma_f32 v98, -v16, v66, v98
	v_fma_f32 v99, -v16, v67, v99
	v_fma_f32 v100, -v16, v26, v100
	v_fma_f32 v101, -v16, v27, v101
	v_fma_f32 v102, -v16, v28, v102
	v_fma_f32 v103, -v16, v29, v103
	v_fma_f32 v104, -v16, v30, v104
	v_fma_f32 v105, -v16, v31, v105
	v_fma_f32 v106, -v16, v32, v106
	v_fma_f32 v107, -v16, v33, v107
	v_fma_f32 v108, -v16, v34, v108
	v_fma_f32 v109, -v16, v35, v109
	ds_read_b128 v[24:27], v11 offset:55072
	ds_read_b128 v[28:31], v11 offset:55088
	ds_read_b128 v[32:35], v11 offset:55104
	ds_read_b128 v[62:65], v11 offset:55120
	v_fma_f32 v110, -v16, v36, v110
	v_fma_f32 v111, -v16, v37, v111
	v_fma_f32 v78, -v16, v78, v112
	v_fma_f32 v79, -v16, v79, v113
	v_fma_f32 v80, -v16, v80, v114
	v_fma_f32 v81, -v16, v81, v115
	v_fma_f32 v112, -v16, v38, v116
	v_fma_f32 v113, -v16, v39, v117
	v_fma_f32 v114, -v16, v40, v118
	v_fma_f32 v115, -v16, v41, v119
	v_fma_f32 v116, -v16, v42, v120
	v_fma_f32 v117, -v16, v43, v121
	v_fma_f32 v118, -v16, v44, v124
	v_fma_f32 v119, -v16, v45, v129
	v_fma_f32 v120, -v16, v46, v130
	v_fma_f32 v121, -v16, v47, v131
	v_fma_f32 v124, -v16, v48, v132
	v_fma_f32 v129, -v16, v49, v133
	ds_read_b128 v[36:39], v11 offset:55136
	ds_read_b128 v[40:43], v11 offset:55152
	ds_read_b128 v[44:47], v11 offset:55168
	ds_read_b128 v[48:51], v11 offset:55184
	v_fma_f32 v130, -v16, v68, v134
	v_fma_f32 v131, -v16, v69, v135
	v_fma_f32 v132, -v16, v70, v76
	v_fma_f32 v133, -v16, v71, v77
	ds_read_b128 v[66:69], v11 offset:55264
	v_fma_f32 v18, -v17, v53, v136
	s_waitcnt lgkmcnt(13)
	v_fma_f32 v134, -v17, v72, v52
	v_fma_f32 v135, -v17, v73, v137
	v_fma_f32 v136, -v17, v74, v138
	v_fma_f32 v137, -v17, v75, v139
	s_waitcnt lgkmcnt(12)
	v_fma_f32 v138, -v17, v20, v140
	v_fma_f32 v139, -v17, v21, v19
	v_fma_f32 v86, -v17, v22, v86
	v_fma_f32 v87, -v17, v23, v87
	s_waitcnt lgkmcnt(11)
	v_fma_f32 v88, -v17, v54, v88
	v_fma_f32 v89, -v17, v55, v89
	v_fma_f32 v90, -v17, v56, v90
	v_fma_f32 v91, -v17, v57, v91
	s_waitcnt lgkmcnt(10)
	v_fma_f32 v92, -v17, v58, v92
	v_fma_f32 v93, -v17, v59, v93
	ds_read_b128 v[20:23], v11 offset:55280
	ds_read_b128 v[52:55], v11 offset:55296
	ds_read_b128 v[56:59], v11 offset:55312
	ds_read_b128 v[70:73], v11 offset:55328
	v_fma_f32 v94, -v17, v60, v94
	v_fma_f32 v95, -v17, v61, v95
	s_waitcnt lgkmcnt(13)
	v_fma_f32 v82, -v17, v82, v96
	v_fma_f32 v83, -v17, v83, v97
	v_fma_f32 v84, -v17, v84, v98
	v_fma_f32 v85, -v17, v85, v99
	s_waitcnt lgkmcnt(12)
	v_fma_f32 v96, -v17, v24, v100
	v_fma_f32 v97, -v17, v25, v101
	v_fma_f32 v98, -v17, v26, v102
	v_fma_f32 v99, -v17, v27, v103
	s_waitcnt lgkmcnt(11)
	v_fma_f32 v100, -v17, v28, v104
	v_fma_f32 v101, -v17, v29, v105
	v_fma_f32 v102, -v17, v30, v106
	v_fma_f32 v103, -v17, v31, v107
	s_waitcnt lgkmcnt(10)
	v_fma_f32 v104, -v17, v32, v108
	v_fma_f32 v105, -v17, v33, v109
	v_fma_f32 v106, -v17, v34, v110
	v_fma_f32 v107, -v17, v35, v111
	ds_read_b128 v[24:27], v11 offset:55344
	ds_read_b128 v[28:31], v11 offset:55360
	ds_read_b128 v[32:35], v11 offset:55376
	ds_read_b128 v[74:77], v11 offset:55392
	s_waitcnt lgkmcnt(13)
	v_fma_f32 v108, -v17, v62, v78
	v_fma_f32 v109, -v17, v63, v79
	v_fma_f32 v110, -v17, v64, v80
	v_fma_f32 v111, -v17, v65, v81
	s_waitcnt lgkmcnt(12)
	v_fma_f32 v112, -v17, v36, v112
	v_fma_f32 v113, -v17, v37, v113
	v_fma_f32 v114, -v17, v38, v114
	v_fma_f32 v115, -v17, v39, v115
	s_waitcnt lgkmcnt(11)
	v_fma_f32 v116, -v17, v40, v116
	v_fma_f32 v117, -v17, v41, v117
	v_fma_f32 v118, -v17, v42, v118
	v_fma_f32 v119, -v17, v43, v119
	s_waitcnt lgkmcnt(10)
	v_fma_f32 v120, -v17, v44, v120
	v_fma_f32 v121, -v17, v45, v121
	v_fma_f32 v124, -v17, v46, v124
	v_fma_f32 v129, -v17, v47, v129
	ds_read_b128 v[36:39], v11 offset:55408
	ds_read_b128 v[40:43], v11 offset:55424
	ds_read_b128 v[44:47], v11 offset:55440
	ds_read_b128 v[60:63], v11 offset:55456
	s_waitcnt lgkmcnt(13)
	v_fma_f32 v130, -v17, v48, v130
	v_fma_f32 v131, -v17, v49, v131
	v_fma_f32 v132, -v17, v50, v132
	v_fma_f32 v133, -v17, v51, v133
	ds_read_b128 v[48:51], v11 offset:55536
	s_waitcnt lgkmcnt(13)
	v_fma_f32 v19, -v18, v66, v134
	s_waitcnt lgkmcnt(0)
	v_fma_f32 v48, -v18, v67, v135
	v_fma_f32 v134, -v18, v68, v136
	v_fma_f32 v135, -v18, v69, v137
	v_fma_f32 v88, -v18, v52, v88
	v_fma_f32 v89, -v18, v53, v89
	v_fma_f32 v90, -v18, v54, v90
	v_fma_f32 v91, -v18, v55, v91
	v_fma_f32 v92, -v18, v56, v92
	v_fma_f32 v93, -v18, v57, v93
	v_fma_f32 v94, -v18, v58, v94
	v_fma_f32 v95, -v18, v59, v95
	ds_read_b128 v[52:55], v11 offset:55552
	ds_read_b128 v[56:59], v11 offset:55568
	ds_read_b128 v[64:67], v11 offset:55584
	ds_read_b128 v[78:81], v11 offset:55600
	v_fma_f32 v136, -v18, v20, v138
	v_fma_f32 v21, -v18, v21, v139
	v_fma_f32 v86, -v18, v22, v86
	v_fma_f32 v87, -v18, v23, v87
	v_fma_f32 v82, -v18, v70, v82
	v_fma_f32 v83, -v18, v71, v83
	v_fma_f32 v84, -v18, v72, v84
	v_fma_f32 v85, -v18, v73, v85
	v_fma_f32 v96, -v18, v24, v96
	v_fma_f32 v97, -v18, v25, v97
	v_fma_f32 v98, -v18, v26, v98
	v_fma_f32 v99, -v18, v27, v99
	v_fma_f32 v100, -v18, v28, v100
	v_fma_f32 v101, -v18, v29, v101
	v_fma_f32 v102, -v18, v30, v102
	v_fma_f32 v103, -v18, v31, v103
	v_fma_f32 v104, -v18, v32, v104
	v_fma_f32 v105, -v18, v33, v105
	ds_read_b128 v[22:25], v11 offset:55616
	ds_read_b128 v[26:29], v11 offset:55632
	ds_read_b128 v[30:33], v11 offset:55648
	ds_read_b128 v[68:71], v11 offset:55664
	v_fma_f32 v106, -v18, v34, v106
	v_fma_f32 v107, -v18, v35, v107
	v_fma_f32 v108, -v18, v74, v108
	v_fma_f32 v109, -v18, v75, v109
	v_fma_f32 v76, -v18, v76, v110
	v_fma_f32 v77, -v18, v77, v111
	v_fma_f32 v110, -v18, v36, v112
	v_fma_f32 v111, -v18, v37, v113
	v_fma_f32 v112, -v18, v38, v114
	v_fma_f32 v113, -v18, v39, v115
	v_fma_f32 v114, -v18, v40, v116
	v_fma_f32 v115, -v18, v41, v117
	v_fma_f32 v116, -v18, v42, v118
	v_fma_f32 v117, -v18, v43, v119
	v_fma_f32 v118, -v18, v44, v120
	v_fma_f32 v119, -v18, v45, v121
	ds_read_b128 v[34:37], v11 offset:55680
	ds_read_b128 v[38:41], v11 offset:55696
	ds_read_b128 v[42:45], v11 offset:55712
	ds_read_b128 v[72:75], v11 offset:55728
	v_fma_f32 v120, -v18, v46, v124
	v_fma_f32 v121, -v18, v47, v129
	v_fma_f32 v124, -v18, v60, v130
	v_fma_f32 v129, -v18, v61, v131
	v_fma_f32 v130, -v18, v62, v132
	v_fma_f32 v131, -v18, v63, v133
	ds_read_b128 v[60:63], v11 offset:55808
	v_fma_f32 v20, -v19, v49, v48
	v_fma_f32 v132, -v19, v50, v134
	v_fma_f32 v133, -v19, v51, v135
	s_waitcnt lgkmcnt(12)
	v_fma_f32 v134, -v19, v52, v136
	v_fma_f32 v135, -v19, v53, v21
	v_fma_f32 v86, -v19, v54, v86
	v_fma_f32 v87, -v19, v55, v87
	s_waitcnt lgkmcnt(11)
	v_fma_f32 v88, -v19, v56, v88
	v_fma_f32 v89, -v19, v57, v89
	v_fma_f32 v90, -v19, v58, v90
	v_fma_f32 v91, -v19, v59, v91
	ds_read_b128 v[46:49], v11 offset:55824
	ds_read_b128 v[50:53], v11 offset:55840
	ds_read_b128 v[54:57], v11 offset:55856
	s_waitcnt lgkmcnt(3)
	ds_read_b128 v[58:61], v11 offset:55872
	v_fma_f32 v92, -v19, v64, v92
	v_fma_f32 v93, -v19, v65, v93
	v_fma_f32 v94, -v19, v66, v94
	v_fma_f32 v95, -v19, v67, v95
	v_fma_f32 v82, -v19, v78, v82
	v_fma_f32 v83, -v19, v79, v83
	v_fma_f32 v80, -v19, v80, v84
	v_fma_f32 v81, -v19, v81, v85
	v_fma_f32 v84, -v19, v22, v96
	v_fma_f32 v85, -v19, v23, v97
	v_fma_f32 v96, -v19, v24, v98
	v_fma_f32 v97, -v19, v25, v99
	v_fma_f32 v98, -v19, v26, v100
	v_fma_f32 v99, -v19, v27, v101
	v_fma_f32 v100, -v19, v28, v102
	v_fma_f32 v101, -v19, v29, v103
	v_fma_f32 v102, -v19, v30, v104
	v_fma_f32 v103, -v19, v31, v105
	v_fma_f32 v104, -v19, v32, v106
	v_fma_f32 v105, -v19, v33, v107
	ds_read_b128 v[22:25], v11 offset:55888
	ds_read_b128 v[26:29], v11 offset:55904
	ds_read_b128 v[30:33], v11 offset:55920
	ds_read_b128 v[64:67], v11 offset:55936
	v_fma_f32 v106, -v19, v68, v108
	v_fma_f32 v107, -v19, v69, v109
	v_fma_f32 v108, -v19, v70, v76
	v_fma_f32 v109, -v19, v71, v77
	v_fma_f32 v110, -v19, v34, v110
	v_fma_f32 v111, -v19, v35, v111
	v_fma_f32 v112, -v19, v36, v112
	v_fma_f32 v113, -v19, v37, v113
	v_fma_f32 v114, -v19, v38, v114
	v_fma_f32 v115, -v19, v39, v115
	v_fma_f32 v116, -v19, v40, v116
	v_fma_f32 v117, -v19, v41, v117
	v_fma_f32 v118, -v19, v42, v118
	v_fma_f32 v119, -v19, v43, v119
	v_fma_f32 v120, -v19, v44, v120
	v_fma_f32 v121, -v19, v45, v121
	ds_read_b128 v[34:37], v11 offset:55952
	ds_read_b128 v[38:41], v11 offset:55968
	ds_read_b128 v[42:45], v11 offset:55984
	ds_read_b128 v[68:71], v11 offset:56000
	v_fma_f32 v124, -v19, v72, v124
	v_fma_f32 v129, -v19, v73, v129
	v_fma_f32 v130, -v19, v74, v130
	v_fma_f32 v131, -v19, v75, v131
	ds_read_b128 v[72:75], v11 offset:56080
	v_fma_f32 v21, -v20, v62, v132
	s_waitcnt lgkmcnt(0)
	v_fma_f32 v72, -v20, v63, v133
	v_fma_f32 v73, -v20, v46, v134
	v_fma_f32 v74, -v20, v47, v135
	v_fma_f32 v86, -v20, v48, v86
	v_fma_f32 v87, -v20, v49, v87
	v_fma_f32 v88, -v20, v50, v88
	v_fma_f32 v89, -v20, v51, v89
	v_fma_f32 v90, -v20, v52, v90
	v_fma_f32 v91, -v20, v53, v91
	v_fma_f32 v92, -v20, v54, v92
	v_fma_f32 v93, -v20, v55, v93
	v_fma_f32 v94, -v20, v56, v94
	v_fma_f32 v95, -v20, v57, v95
	ds_read_b128 v[46:49], v11 offset:56096
	ds_read_b128 v[50:53], v11 offset:56112
	ds_read_b128 v[54:57], v11 offset:56128
	ds_read_b128 v[76:79], v11 offset:56144
	v_fma_f32 v132, -v20, v58, v82
	v_fma_f32 v133, -v20, v59, v83
	v_fma_f32 v134, -v20, v60, v80
	v_fma_f32 v135, -v20, v61, v81
	v_fma_f32 v23, -v20, v23, v85
	v_fma_f32 v85, -v20, v24, v96
	v_fma_f32 v96, -v20, v25, v97
	v_fma_f32 v97, -v20, v26, v98
	v_fma_f32 v98, -v20, v27, v99
	v_fma_f32 v99, -v20, v28, v100
	v_fma_f32 v100, -v20, v29, v101
	v_fma_f32 v101, -v20, v30, v102
	v_fma_f32 v102, -v20, v31, v103
	ds_read_b128 v[24:27], v11 offset:56160
	ds_read_b128 v[28:31], v11 offset:56176
	ds_read_b128 v[58:61], v11 offset:56192
	ds_read_b128 v[80:83], v11 offset:56208
	v_fma_f32 v84, -v20, v22, v84
	v_fma_f32 v103, -v20, v32, v104
	v_fma_f32 v104, -v20, v33, v105
	v_fma_f32 v105, -v20, v64, v106
	v_fma_f32 v106, -v20, v65, v107
	v_fma_f32 v107, -v20, v66, v108
	v_fma_f32 v108, -v20, v67, v109
	v_fma_f32 v109, -v20, v34, v110
	v_fma_f32 v110, -v20, v35, v111
	v_fma_f32 v111, -v20, v36, v112
	v_fma_f32 v112, -v20, v37, v113
	v_fma_f32 v113, -v20, v38, v114
	v_fma_f32 v114, -v20, v39, v115
	v_fma_f32 v115, -v20, v40, v116
	v_fma_f32 v116, -v20, v41, v117
	v_fma_f32 v117, -v20, v42, v118
	v_fma_f32 v118, -v20, v43, v119
	ds_read_b128 v[32:35], v11 offset:56224
	ds_read_b128 v[36:39], v11 offset:56240
	ds_read_b128 v[40:43], v11 offset:56256
	ds_read_b128 v[62:65], v11 offset:56272
	v_fma_f32 v119, -v20, v44, v120
	v_fma_f32 v120, -v20, v45, v121
	v_fma_f32 v121, -v20, v68, v124
	v_fma_f32 v124, -v20, v69, v129
	v_fma_f32 v129, -v20, v70, v130
	v_fma_f32 v130, -v20, v71, v131
	v_fma_f32 v22, -v21, v75, v72
	s_waitcnt lgkmcnt(11)
	v_fma_f32 v131, -v21, v46, v73
	v_fma_f32 v136, -v21, v47, v74
	v_fma_f32 v86, -v21, v48, v86
	v_fma_f32 v87, -v21, v49, v87
	s_waitcnt lgkmcnt(10)
	v_fma_f32 v88, -v21, v50, v88
	v_fma_f32 v89, -v21, v51, v89
	v_fma_f32 v90, -v21, v52, v90
	v_fma_f32 v91, -v21, v53, v91
	s_waitcnt lgkmcnt(9)
	v_fma_f32 v92, -v21, v54, v92
	v_fma_f32 v93, -v21, v55, v93
	ds_read_b128 v[44:47], v11 offset:56368
	ds_read_b128 v[48:51], v11 offset:56384
	ds_read_b128 v[52:55], v11 offset:56400
	ds_read_b128 v[66:69], v11 offset:56416
	v_fma_f32 v94, -v21, v56, v94
	v_fma_f32 v95, -v21, v57, v95
	s_waitcnt lgkmcnt(12)
	v_fma_f32 v132, -v21, v76, v132
	v_fma_f32 v133, -v21, v77, v133
	v_fma_f32 v78, -v21, v78, v134
	v_fma_f32 v79, -v21, v79, v135
	s_waitcnt lgkmcnt(11)
	v_fma_f32 v84, -v21, v24, v84
	v_fma_f32 v134, -v21, v25, v23
	v_fma_f32 v85, -v21, v26, v85
	v_fma_f32 v96, -v21, v27, v96
	s_waitcnt lgkmcnt(10)
	v_fma_f32 v97, -v21, v28, v97
	v_fma_f32 v98, -v21, v29, v98
	v_fma_f32 v99, -v21, v30, v99
	v_fma_f32 v100, -v21, v31, v100
	s_waitcnt lgkmcnt(9)
	v_fma_f32 v101, -v21, v58, v101
	v_fma_f32 v102, -v21, v59, v102
	ds_read_b128 v[24:27], v11 offset:56432
	ds_read_b128 v[28:31], v11 offset:56448
	ds_read_b128 v[56:59], v11 offset:56464
	ds_read_b128 v[70:73], v11 offset:56480
	v_fma_f32 v103, -v21, v60, v103
	v_fma_f32 v104, -v21, v61, v104
	s_waitcnt lgkmcnt(12)
	v_fma_f32 v105, -v21, v80, v105
	v_fma_f32 v106, -v21, v81, v106
	v_fma_f32 v82, -v21, v82, v107
	v_fma_f32 v83, -v21, v83, v108
	s_waitcnt lgkmcnt(11)
	v_fma_f32 v107, -v21, v32, v109
	v_fma_f32 v108, -v21, v33, v110
	v_fma_f32 v109, -v21, v34, v111
	v_fma_f32 v110, -v21, v35, v112
	s_waitcnt lgkmcnt(10)
	v_fma_f32 v111, -v21, v36, v113
	v_fma_f32 v112, -v21, v37, v114
	v_fma_f32 v113, -v21, v38, v115
	v_fma_f32 v114, -v21, v39, v116
	s_waitcnt lgkmcnt(9)
	v_fma_f32 v115, -v21, v40, v117
	v_fma_f32 v116, -v21, v41, v118
	v_fma_f32 v117, -v21, v42, v119
	v_fma_f32 v118, -v21, v43, v120
	ds_read_b128 v[32:35], v11 offset:56496
	ds_read_b128 v[36:39], v11 offset:56512
	ds_read_b128 v[40:43], v11 offset:56528
	ds_read_b128 v[74:77], v11 offset:56544
	s_waitcnt lgkmcnt(12)
	v_fma_f32 v119, -v21, v62, v121
	v_fma_f32 v120, -v21, v63, v124
	v_fma_f32 v121, -v21, v64, v129
	v_fma_f32 v124, -v21, v65, v130
	s_waitcnt lgkmcnt(11)
	v_fma_f32 v23, -v22, v44, v131
	v_fma_f32 v129, -v22, v45, v136
	v_fma_f32 v86, -v22, v46, v86
	v_fma_f32 v87, -v22, v47, v87
	s_waitcnt lgkmcnt(10)
	v_fma_f32 v88, -v22, v48, v88
	v_fma_f32 v89, -v22, v49, v89
	v_fma_f32 v90, -v22, v50, v90
	v_fma_f32 v91, -v22, v51, v91
	s_waitcnt lgkmcnt(9)
	v_fma_f32 v92, -v22, v52, v92
	v_fma_f32 v93, -v22, v53, v93
	v_fma_f32 v94, -v22, v54, v94
	v_fma_f32 v95, -v22, v55, v95
	ds_read_b128 v[44:47], v11 offset:56640
	ds_read_b128 v[48:51], v11 offset:56656
	ds_read_b128 v[52:55], v11 offset:56672
	ds_read_b128 v[60:63], v11 offset:56688
	s_waitcnt lgkmcnt(12)
	v_fma_f32 v130, -v22, v66, v132
	v_fma_f32 v131, -v22, v67, v133
	v_fma_f32 v132, -v22, v68, v78
	v_fma_f32 v133, -v22, v69, v79
	s_waitcnt lgkmcnt(11)
	v_fma_f32 v85, -v22, v26, v85
	v_fma_f32 v96, -v22, v27, v96
	s_waitcnt lgkmcnt(10)
	v_fma_f32 v97, -v22, v28, v97
	v_fma_f32 v98, -v22, v29, v98
	s_waitcnt lgkmcnt(9)
	v_fma_f32 v101, -v22, v56, v101
	v_fma_f32 v102, -v22, v57, v102
	v_fma_f32 v103, -v22, v58, v103
	v_fma_f32 v104, -v22, v59, v104
	ds_read_b128 v[26:29], v11 offset:56704
	ds_read_b128 v[56:59], v11 offset:56720
	ds_read_b128 v[64:67], v11 offset:56736
	ds_read_b128 v[78:81], v11 offset:56752
	v_fma_f32 v84, -v22, v24, v84
	v_fma_f32 v25, -v22, v25, v134
	v_fma_f32 v99, -v22, v30, v99
	v_fma_f32 v100, -v22, v31, v100
	s_waitcnt lgkmcnt(12)
	v_fma_f32 v105, -v22, v70, v105
	v_fma_f32 v106, -v22, v71, v106
	v_fma_f32 v82, -v22, v72, v82
	v_fma_f32 v83, -v22, v73, v83
	s_waitcnt lgkmcnt(11)
	v_fma_f32 v107, -v22, v32, v107
	v_fma_f32 v108, -v22, v33, v108
	v_fma_f32 v109, -v22, v34, v109
	v_fma_f32 v110, -v22, v35, v110
	s_waitcnt lgkmcnt(10)
	v_fma_f32 v111, -v22, v36, v111
	v_fma_f32 v112, -v22, v37, v112
	v_fma_f32 v113, -v22, v38, v113
	v_fma_f32 v114, -v22, v39, v114
	s_waitcnt lgkmcnt(9)
	v_fma_f32 v115, -v22, v40, v115
	v_fma_f32 v116, -v22, v41, v116
	ds_read_b128 v[30:33], v11 offset:56768
	ds_read_b128 v[34:37], v11 offset:56784
	ds_read_b128 v[38:41], v11 offset:56800
	ds_read_b128 v[68:71], v11 offset:56816
	v_fma_f32 v117, -v22, v42, v117
	v_fma_f32 v118, -v22, v43, v118
	s_waitcnt lgkmcnt(12)
	v_fma_f32 v119, -v22, v74, v119
	v_fma_f32 v120, -v22, v75, v120
	v_fma_f32 v121, -v22, v76, v121
	v_fma_f32 v124, -v22, v77, v124
	s_waitcnt lgkmcnt(11)
	v_fma_f32 v24, -v23, v45, v129
	v_fma_f32 v86, -v23, v46, v86
	v_fma_f32 v87, -v23, v47, v87
	s_waitcnt lgkmcnt(10)
	v_fma_f32 v88, -v23, v48, v88
	v_fma_f32 v89, -v23, v49, v89
	v_fma_f32 v90, -v23, v50, v90
	v_fma_f32 v91, -v23, v51, v91
	s_waitcnt lgkmcnt(9)
	v_fma_f32 v92, -v23, v52, v92
	v_fma_f32 v93, -v23, v53, v93
	ds_read_b128 v[42:45], v11 offset:56912
	ds_read_b128 v[46:49], v11 offset:56928
	ds_read_b128 v[50:53], v11 offset:56944
	ds_read_b128 v[72:75], v11 offset:56960
	v_fma_f32 v94, -v23, v54, v94
	v_fma_f32 v95, -v23, v55, v95
	s_waitcnt lgkmcnt(12)
	v_fma_f32 v129, -v23, v60, v130
	v_fma_f32 v130, -v23, v61, v131
	v_fma_f32 v131, -v23, v62, v132
	v_fma_f32 v132, -v23, v63, v133
	s_waitcnt lgkmcnt(11)
	v_fma_f32 v84, -v23, v26, v84
	v_fma_f32 v133, -v23, v27, v25
	v_fma_f32 v85, -v23, v28, v85
	v_fma_f32 v96, -v23, v29, v96
	s_waitcnt lgkmcnt(10)
	v_fma_f32 v97, -v23, v56, v97
	v_fma_f32 v98, -v23, v57, v98
	v_fma_f32 v99, -v23, v58, v99
	v_fma_f32 v100, -v23, v59, v100
	s_waitcnt lgkmcnt(9)
	v_fma_f32 v101, -v23, v64, v101
	v_fma_f32 v102, -v23, v65, v102
	ds_read_b128 v[26:29], v11 offset:56976
	ds_read_b128 v[54:57], v11 offset:56992
	ds_read_b128 v[58:61], v11 offset:57008
	ds_read_b128 v[62:65], v11 offset:57024
	v_fma_f32 v103, -v23, v66, v103
	v_fma_f32 v104, -v23, v67, v104
	s_waitcnt lgkmcnt(12)
	v_fma_f32 v105, -v23, v78, v105
	v_fma_f32 v106, -v23, v79, v106
	v_fma_f32 v134, -v23, v80, v82
	v_fma_f32 v135, -v23, v81, v83
	s_waitcnt lgkmcnt(11)
	v_fma_f32 v107, -v23, v30, v107
	v_fma_f32 v108, -v23, v31, v108
	v_fma_f32 v109, -v23, v32, v109
	v_fma_f32 v110, -v23, v33, v110
	s_waitcnt lgkmcnt(10)
	v_fma_f32 v111, -v23, v34, v111
	v_fma_f32 v112, -v23, v35, v112
	v_fma_f32 v113, -v23, v36, v113
	v_fma_f32 v114, -v23, v37, v114
	s_waitcnt lgkmcnt(9)
	v_fma_f32 v115, -v23, v38, v115
	v_fma_f32 v116, -v23, v39, v116
	v_fma_f32 v117, -v23, v40, v117
	v_fma_f32 v118, -v23, v41, v118
	ds_read_b128 v[30:33], v11 offset:57040
	ds_read_b128 v[34:37], v11 offset:57056
	ds_read_b128 v[38:41], v11 offset:57072
	ds_read_b128 v[76:79], v11 offset:57088
	s_waitcnt lgkmcnt(12)
	v_fma_f32 v119, -v23, v68, v119
	v_fma_f32 v120, -v23, v69, v120
	v_fma_f32 v121, -v23, v70, v121
	v_fma_f32 v124, -v23, v71, v124
	s_waitcnt lgkmcnt(11)
	v_fma_f32 v25, -v24, v44, v86
	v_fma_f32 v86, -v24, v45, v87
	s_waitcnt lgkmcnt(10)
	v_fma_f32 v87, -v24, v46, v88
	v_fma_f32 v88, -v24, v47, v89
	v_fma_f32 v89, -v24, v48, v90
	v_fma_f32 v90, -v24, v49, v91
	s_waitcnt lgkmcnt(9)
	v_fma_f32 v91, -v24, v50, v92
	v_fma_f32 v92, -v24, v51, v93
	v_fma_f32 v93, -v24, v52, v94
	v_fma_f32 v94, -v24, v53, v95
	ds_read_b128 v[42:45], v11 offset:57184
	ds_read_b128 v[46:49], v11 offset:57200
	ds_read_b128 v[50:53], v11 offset:57216
	ds_read_b128 v[66:69], v11 offset:57232
	s_waitcnt lgkmcnt(12)
	v_fma_f32 v95, -v24, v72, v129
	v_fma_f32 v129, -v24, v73, v130
	v_fma_f32 v74, -v24, v74, v131
	v_fma_f32 v75, -v24, v75, v132
	s_waitcnt lgkmcnt(10)
	v_fma_f32 v97, -v24, v54, v97
	v_fma_f32 v98, -v24, v55, v98
	v_fma_f32 v99, -v24, v56, v99
	v_fma_f32 v100, -v24, v57, v100
	s_waitcnt lgkmcnt(9)
	v_fma_f32 v101, -v24, v58, v101
	v_fma_f32 v102, -v24, v59, v102
	v_fma_f32 v103, -v24, v60, v103
	v_fma_f32 v104, -v24, v61, v104
	ds_read_b128 v[54:57], v11 offset:57248
	ds_read_b128 v[58:61], v11 offset:57264
	ds_read_b128 v[70:73], v11 offset:57280
	ds_read_b128 v[80:83], v11 offset:57296
	v_fma_f32 v84, -v24, v26, v84
	v_fma_f32 v27, -v24, v27, v133
	v_fma_f32 v85, -v24, v28, v85
	v_fma_f32 v96, -v24, v29, v96
	s_waitcnt lgkmcnt(12)
	v_fma_f32 v105, -v24, v62, v105
	v_fma_f32 v106, -v24, v63, v106
	v_fma_f32 v130, -v24, v64, v134
	v_fma_f32 v131, -v24, v65, v135
	s_waitcnt lgkmcnt(11)
	v_fma_f32 v107, -v24, v30, v107
	v_fma_f32 v108, -v24, v31, v108
	v_fma_f32 v109, -v24, v32, v109
	v_fma_f32 v110, -v24, v33, v110
	s_waitcnt lgkmcnt(10)
	v_fma_f32 v111, -v24, v34, v111
	v_fma_f32 v112, -v24, v35, v112
	v_fma_f32 v113, -v24, v36, v113
	v_fma_f32 v114, -v24, v37, v114
	s_waitcnt lgkmcnt(9)
	v_fma_f32 v115, -v24, v38, v115
	v_fma_f32 v116, -v24, v39, v116
	v_fma_f32 v117, -v24, v40, v117
	v_fma_f32 v118, -v24, v41, v118
	ds_read_b128 v[28:31], v11 offset:57312
	ds_read_b128 v[32:35], v11 offset:57328
	ds_read_b128 v[36:39], v11 offset:57344
	s_waitcnt lgkmcnt(10)
	ds_read_b128 v[40:43], v11 offset:57360
	v_fma_f32 v119, -v24, v76, v119
	v_fma_f32 v120, -v24, v77, v120
	v_fma_f32 v78, -v24, v78, v121
	v_fma_f32 v79, -v24, v79, v124
	v_fma_f32 v26, -v25, v45, v86
	s_waitcnt lgkmcnt(10)
	v_fma_f32 v86, -v25, v46, v87
	v_fma_f32 v87, -v25, v47, v88
	v_fma_f32 v88, -v25, v48, v89
	v_fma_f32 v89, -v25, v49, v90
	s_waitcnt lgkmcnt(9)
	v_fma_f32 v90, -v25, v50, v91
	v_fma_f32 v91, -v25, v51, v92
	ds_read_b128 v[44:47], v11 offset:57472
	ds_read_b128 v[48:51], v11 offset:57488
	ds_read_b128 v[62:65], v11 offset:57504
	v_fma_f32 v92, -v25, v52, v93
	v_fma_f32 v93, -v25, v53, v94
	s_waitcnt lgkmcnt(11)
	v_fma_f32 v94, -v25, v66, v95
	v_fma_f32 v95, -v25, v67, v129
	v_fma_f32 v121, -v25, v68, v74
	v_fma_f32 v124, -v25, v69, v75
	s_waitcnt lgkmcnt(10)
	v_fma_f32 v84, -v25, v54, v84
	v_fma_f32 v129, -v25, v55, v27
	v_fma_f32 v85, -v25, v56, v85
	v_fma_f32 v96, -v25, v57, v96
	s_waitcnt lgkmcnt(9)
	v_fma_f32 v97, -v25, v58, v97
	v_fma_f32 v98, -v25, v59, v98
	v_fma_f32 v60, -v25, v60, v99
	v_fma_f32 v61, -v25, v61, v100
	s_waitcnt lgkmcnt(8)
	v_fma_f32 v99, -v25, v70, v101
	v_fma_f32 v100, -v25, v71, v102
	v_fma_f32 v101, -v25, v72, v103
	v_fma_f32 v102, -v25, v73, v104
	ds_read_b128 v[52:55], v11 offset:57520
	ds_read_b128 v[56:59], v11 offset:57536
	ds_read_b128 v[66:69], v11 offset:57552
	ds_read_b128 v[70:73], v11 offset:57568
	s_waitcnt lgkmcnt(11)
	v_fma_f32 v80, -v25, v80, v105
	v_fma_f32 v81, -v25, v81, v106
	v_fma_f32 v82, -v25, v82, v130
	v_fma_f32 v83, -v25, v83, v131
	s_waitcnt lgkmcnt(10)
	v_fma_f32 v103, -v25, v28, v107
	v_fma_f32 v104, -v25, v29, v108
	v_fma_f32 v105, -v25, v30, v109
	v_fma_f32 v106, -v25, v31, v110
	s_waitcnt lgkmcnt(9)
	v_fma_f32 v107, -v25, v32, v111
	v_fma_f32 v108, -v25, v33, v112
	v_fma_f32 v109, -v25, v34, v113
	v_fma_f32 v110, -v25, v35, v114
	s_waitcnt lgkmcnt(8)
	v_fma_f32 v111, -v25, v36, v115
	v_fma_f32 v112, -v25, v37, v116
	v_fma_f32 v113, -v25, v38, v117
	v_fma_f32 v114, -v25, v39, v118
	ds_read_b128 v[28:31], v11 offset:57584
	ds_read_b128 v[32:35], v11 offset:57600
	ds_read_b128 v[36:39], v11 offset:57616
	ds_read_b128 v[74:77], v11 offset:57632
	s_waitcnt lgkmcnt(11)
	v_fma_f32 v115, -v25, v40, v119
	v_fma_f32 v116, -v25, v41, v120
	v_fma_f32 v117, -v25, v42, v78
	v_fma_f32 v118, -v25, v43, v79
	s_waitcnt lgkmcnt(10)
	v_fma_f32 v27, -v26, v44, v86
	v_fma_f32 v86, -v26, v45, v87
	v_fma_f32 v87, -v26, v46, v88
	v_fma_f32 v88, -v26, v47, v89
	s_waitcnt lgkmcnt(9)
	v_fma_f32 v89, -v26, v48, v90
	v_fma_f32 v90, -v26, v49, v91
	v_fma_f32 v91, -v26, v50, v92
	v_fma_f32 v92, -v26, v51, v93
	ds_read_b128 v[40:43], v11 offset:57744
	ds_read_b128 v[44:47], v11 offset:57760
	ds_read_b128 v[48:51], v11 offset:57776
	s_waitcnt lgkmcnt(11)
	v_fma_f32 v93, -v26, v62, v94
	v_fma_f32 v94, -v26, v63, v95
	v_fma_f32 v95, -v26, v64, v121
	v_fma_f32 v119, -v26, v65, v124
	s_waitcnt lgkmcnt(10)
	v_fma_f32 v84, -v26, v52, v84
	v_fma_f32 v120, -v26, v53, v129
	v_fma_f32 v85, -v26, v54, v85
	v_fma_f32 v96, -v26, v55, v96
	s_waitcnt lgkmcnt(9)
	v_fma_f32 v97, -v26, v56, v97
	v_fma_f32 v98, -v26, v57, v98
	v_fma_f32 v121, -v26, v58, v60
	v_fma_f32 v124, -v26, v59, v61
	s_waitcnt lgkmcnt(8)
	v_fma_f32 v99, -v26, v66, v99
	v_fma_f32 v100, -v26, v67, v100
	ds_read_b128 v[52:55], v11 offset:57792
	ds_read_b128 v[56:59], v11 offset:57808
	ds_read_b128 v[60:63], v11 offset:57824
	ds_read_b128 v[64:67], v11 offset:57840
	v_fma_f32 v101, -v26, v68, v101
	v_fma_f32 v102, -v26, v69, v102
	s_waitcnt lgkmcnt(11)
	v_fma_f32 v129, -v26, v70, v80
	v_fma_f32 v130, -v26, v71, v81
	v_fma_f32 v82, -v26, v72, v82
	v_fma_f32 v83, -v26, v73, v83
	s_waitcnt lgkmcnt(10)
	v_fma_f32 v29, -v26, v29, v104
	v_fma_f32 v104, -v26, v30, v105
	v_fma_f32 v105, -v26, v31, v106
	s_waitcnt lgkmcnt(9)
	v_fma_f32 v106, -v26, v32, v107
	v_fma_f32 v107, -v26, v33, v108
	v_fma_f32 v108, -v26, v34, v109
	v_fma_f32 v109, -v26, v35, v110
	s_waitcnt lgkmcnt(8)
	v_fma_f32 v110, -v26, v36, v111
	v_fma_f32 v111, -v26, v37, v112
	ds_read_b128 v[30:33], v11 offset:57856
	ds_read_b128 v[34:37], v11 offset:57872
	ds_read_b128 v[68:71], v11 offset:57888
	ds_read_b128 v[78:81], v11 offset:57904
	v_fma_f32 v103, -v26, v28, v103
	v_fma_f32 v112, -v26, v38, v113
	v_fma_f32 v113, -v26, v39, v114
	s_waitcnt lgkmcnt(11)
	v_fma_f32 v114, -v26, v74, v115
	v_fma_f32 v115, -v26, v75, v116
	v_fma_f32 v76, -v26, v76, v117
	v_fma_f32 v77, -v26, v77, v118
	s_waitcnt lgkmcnt(10)
	v_fma_f32 v28, -v27, v41, v86
	v_fma_f32 v86, -v27, v42, v87
	v_fma_f32 v87, -v27, v43, v88
	s_waitcnt lgkmcnt(9)
	v_fma_f32 v88, -v27, v44, v89
	v_fma_f32 v89, -v27, v45, v90
	ds_read_b128 v[38:41], v11 offset:58016
	ds_read_b128 v[42:45], v11 offset:58032
	ds_read_b128 v[72:75], v11 offset:58048
	v_fma_f32 v90, -v27, v46, v91
	v_fma_f32 v91, -v27, v47, v92
	s_waitcnt lgkmcnt(11)
	v_fma_f32 v92, -v27, v48, v93
	v_fma_f32 v93, -v27, v49, v94
	v_fma_f32 v94, -v27, v50, v95
	v_fma_f32 v95, -v27, v51, v119
	s_waitcnt lgkmcnt(10)
	v_fma_f32 v84, -v27, v52, v84
	v_fma_f32 v116, -v27, v53, v120
	v_fma_f32 v85, -v27, v54, v85
	v_fma_f32 v96, -v27, v55, v96
	s_waitcnt lgkmcnt(9)
	v_fma_f32 v97, -v27, v56, v97
	v_fma_f32 v98, -v27, v57, v98
	v_fma_f32 v117, -v27, v58, v121
	v_fma_f32 v118, -v27, v59, v124
	s_waitcnt lgkmcnt(8)
	v_fma_f32 v99, -v27, v60, v99
	v_fma_f32 v100, -v27, v61, v100
	ds_read_b128 v[46:49], v11 offset:58064
	ds_read_b128 v[50:53], v11 offset:58080
	ds_read_b128 v[54:57], v11 offset:58096
	ds_read_b128 v[58:61], v11 offset:58112
	v_fma_f32 v101, -v27, v62, v101
	v_fma_f32 v102, -v27, v63, v102
	s_waitcnt lgkmcnt(11)
	v_fma_f32 v119, -v27, v64, v129
	v_fma_f32 v120, -v27, v65, v130
	v_fma_f32 v82, -v27, v66, v82
	v_fma_f32 v83, -v27, v67, v83
	s_waitcnt lgkmcnt(10)
	v_fma_f32 v103, -v27, v30, v103
	v_fma_f32 v121, -v27, v31, v29
	v_fma_f32 v104, -v27, v32, v104
	v_fma_f32 v105, -v27, v33, v105
	s_waitcnt lgkmcnt(9)
	v_fma_f32 v106, -v27, v34, v106
	v_fma_f32 v107, -v27, v35, v107
	v_fma_f32 v108, -v27, v36, v108
	v_fma_f32 v109, -v27, v37, v109
	s_waitcnt lgkmcnt(8)
	v_fma_f32 v110, -v27, v68, v110
	v_fma_f32 v111, -v27, v69, v111
	ds_read_b128 v[30:33], v11 offset:58128
	ds_read_b128 v[34:37], v11 offset:58144
	ds_read_b128 v[62:65], v11 offset:58160
	ds_read_b128 v[66:69], v11 offset:58176
	v_fma_f32 v112, -v27, v70, v112
	v_fma_f32 v113, -v27, v71, v113
	s_waitcnt lgkmcnt(11)
	v_fma_f32 v114, -v27, v78, v114
	v_fma_f32 v115, -v27, v79, v115
	v_fma_f32 v80, -v27, v80, v76
	v_fma_f32 v81, -v27, v81, v77
	s_waitcnt lgkmcnt(10)
	v_fma_f32 v29, -v28, v40, v86
	v_fma_f32 v86, -v28, v41, v87
	s_waitcnt lgkmcnt(9)
	v_fma_f32 v87, -v28, v42, v88
	v_fma_f32 v88, -v28, v43, v89
	v_fma_f32 v89, -v28, v44, v90
	v_fma_f32 v90, -v28, v45, v91
	ds_read_b128 v[38:41], v11 offset:58288
	ds_read_b128 v[42:45], v11 offset:58304
	ds_read_b128 v[76:79], v11 offset:58320
	s_waitcnt lgkmcnt(11)
	v_fma_f32 v91, -v28, v72, v92
	v_fma_f32 v92, -v28, v73, v93
	v_fma_f32 v74, -v28, v74, v94
	v_fma_f32 v75, -v28, v75, v95
	s_waitcnt lgkmcnt(10)
	v_fma_f32 v84, -v28, v46, v84
	v_fma_f32 v93, -v28, v47, v116
	v_fma_f32 v85, -v28, v48, v85
	v_fma_f32 v94, -v28, v49, v96
	s_waitcnt lgkmcnt(9)
	v_fma_f32 v95, -v28, v50, v97
	v_fma_f32 v96, -v28, v51, v98
	v_fma_f32 v97, -v28, v52, v117
	v_fma_f32 v98, -v28, v53, v118
	s_waitcnt lgkmcnt(8)
	v_fma_f32 v99, -v28, v54, v99
	v_fma_f32 v100, -v28, v55, v100
	v_fma_f32 v101, -v28, v56, v101
	v_fma_f32 v102, -v28, v57, v102
	ds_read_b128 v[46:49], v11 offset:58336
	ds_read_b128 v[50:53], v11 offset:58352
	ds_read_b128 v[54:57], v11 offset:58368
	ds_read_b128 v[70:73], v11 offset:58384
	s_waitcnt lgkmcnt(11)
	v_fma_f32 v116, -v28, v58, v119
	v_fma_f32 v117, -v28, v59, v120
	v_fma_f32 v82, -v28, v60, v82
	v_fma_f32 v83, -v28, v61, v83
	s_waitcnt lgkmcnt(10)
	v_fma_f32 v104, -v28, v32, v104
	v_fma_f32 v105, -v28, v33, v105
	s_waitcnt lgkmcnt(9)
	v_fma_f32 v106, -v28, v34, v106
	v_fma_f32 v107, -v28, v35, v107
	v_fma_f32 v108, -v28, v36, v108
	v_fma_f32 v109, -v28, v37, v109
	s_waitcnt lgkmcnt(8)
	v_fma_f32 v110, -v28, v62, v110
	v_fma_f32 v111, -v28, v63, v111
	v_fma_f32 v112, -v28, v64, v112
	v_fma_f32 v113, -v28, v65, v113
	ds_read_b128 v[32:35], v11 offset:58400
	s_waitcnt lgkmcnt(7)
	ds_read_b128 v[36:39], v11 offset:58416
	ds_read_b128 v[58:61], v11 offset:58432
	ds_read_b128 v[62:65], v11 offset:58448
	v_fma_f32 v103, -v28, v30, v103
	v_fma_f32 v31, -v28, v31, v121
	v_fma_f32 v114, -v28, v66, v114
	v_fma_f32 v115, -v28, v67, v115
	v_fma_f32 v80, -v28, v68, v80
	v_fma_f32 v81, -v28, v69, v81
	v_fma_f32 v30, -v29, v41, v86
	s_waitcnt lgkmcnt(9)
	v_fma_f32 v86, -v29, v42, v87
	v_fma_f32 v87, -v29, v43, v88
	ds_read_b128 v[40:43], v11 offset:58576
	ds_read_b128 v[66:69], v11 offset:58592
	v_fma_f32 v88, -v29, v44, v89
	v_fma_f32 v89, -v29, v45, v90
	s_waitcnt lgkmcnt(10)
	v_fma_f32 v90, -v29, v76, v91
	v_fma_f32 v91, -v29, v77, v92
	v_fma_f32 v78, -v29, v78, v74
	v_fma_f32 v79, -v29, v79, v75
	s_waitcnt lgkmcnt(9)
	v_fma_f32 v84, -v29, v46, v84
	v_fma_f32 v92, -v29, v47, v93
	v_fma_f32 v85, -v29, v48, v85
	v_fma_f32 v93, -v29, v49, v94
	s_waitcnt lgkmcnt(8)
	v_fma_f32 v94, -v29, v50, v95
	v_fma_f32 v95, -v29, v51, v96
	v_fma_f32 v96, -v29, v52, v97
	v_fma_f32 v97, -v29, v53, v98
	s_waitcnt lgkmcnt(7)
	v_fma_f32 v98, -v29, v54, v99
	v_fma_f32 v99, -v29, v55, v100
	ds_read_b128 v[44:47], v11 offset:58608
	ds_read_b128 v[48:51], v11 offset:58624
	ds_read_b128 v[52:55], v11 offset:58640
	ds_read_b128 v[74:77], v11 offset:58656
	v_fma_f32 v100, -v29, v56, v101
	v_fma_f32 v101, -v29, v57, v102
	s_waitcnt lgkmcnt(10)
	v_fma_f32 v102, -v29, v70, v116
	v_fma_f32 v116, -v29, v71, v117
	v_fma_f32 v82, -v29, v72, v82
	v_fma_f32 v83, -v29, v73, v83
	s_waitcnt lgkmcnt(9)
	v_fma_f32 v103, -v29, v32, v103
	v_fma_f32 v117, -v29, v33, v31
	v_fma_f32 v104, -v29, v34, v104
	v_fma_f32 v105, -v29, v35, v105
	s_waitcnt lgkmcnt(8)
	v_fma_f32 v106, -v29, v36, v106
	v_fma_f32 v107, -v29, v37, v107
	v_fma_f32 v108, -v29, v38, v108
	v_fma_f32 v109, -v29, v39, v109
	s_waitcnt lgkmcnt(7)
	v_fma_f32 v110, -v29, v58, v110
	v_fma_f32 v111, -v29, v59, v111
	ds_read_b128 v[32:35], v11 offset:58672
	ds_read_b128 v[36:39], v11 offset:58688
	ds_read_b128 v[56:59], v11 offset:58704
	ds_read_b128 v[70:73], v11 offset:58720
	v_fma_f32 v112, -v29, v60, v112
	v_fma_f32 v113, -v29, v61, v113
	s_waitcnt lgkmcnt(10)
	v_fma_f32 v114, -v29, v62, v114
	v_fma_f32 v115, -v29, v63, v115
	v_fma_f32 v118, -v29, v64, v80
	v_fma_f32 v119, -v29, v65, v81
	s_waitcnt lgkmcnt(9)
	v_fma_f32 v31, -v30, v40, v86
	v_fma_f32 v86, -v30, v41, v87
	v_fma_f32 v87, -v30, v42, v88
	v_fma_f32 v88, -v30, v43, v89
	ds_read_b128 v[40:43], v11 offset:58848
	ds_read_b128 v[60:63], v11 offset:58864
	s_waitcnt lgkmcnt(10)
	v_fma_f32 v89, -v30, v66, v90
	v_fma_f32 v90, -v30, v67, v91
	v_fma_f32 v91, -v30, v68, v78
	v_fma_f32 v120, -v30, v69, v79
	s_waitcnt lgkmcnt(9)
	v_fma_f32 v84, -v30, v44, v84
	v_fma_f32 v92, -v30, v45, v92
	v_fma_f32 v85, -v30, v46, v85
	v_fma_f32 v93, -v30, v47, v93
	s_waitcnt lgkmcnt(8)
	v_fma_f32 v94, -v30, v48, v94
	v_fma_f32 v95, -v30, v49, v95
	v_fma_f32 v96, -v30, v50, v96
	v_fma_f32 v97, -v30, v51, v97
	s_waitcnt lgkmcnt(7)
	v_fma_f32 v98, -v30, v52, v98
	v_fma_f32 v99, -v30, v53, v99
	v_fma_f32 v100, -v30, v54, v100
	v_fma_f32 v101, -v30, v55, v101
	ds_read_b128 v[44:47], v11 offset:58880
	ds_read_b128 v[48:51], v11 offset:58896
	ds_read_b128 v[52:55], v11 offset:58912
	ds_read_b128 v[64:67], v11 offset:58928
	s_waitcnt lgkmcnt(10)
	v_fma_f32 v102, -v30, v74, v102
	v_fma_f32 v116, -v30, v75, v116
	v_fma_f32 v82, -v30, v76, v82
	v_fma_f32 v83, -v30, v77, v83
	s_waitcnt lgkmcnt(9)
	v_fma_f32 v104, -v30, v34, v104
	v_fma_f32 v105, -v30, v35, v105
	s_waitcnt lgkmcnt(8)
	v_fma_f32 v106, -v30, v36, v106
	v_fma_f32 v107, -v30, v37, v107
	s_waitcnt lgkmcnt(7)
	v_fma_f32 v110, -v30, v56, v110
	v_fma_f32 v111, -v30, v57, v111
	v_fma_f32 v112, -v30, v58, v112
	v_fma_f32 v113, -v30, v59, v113
	ds_read_b128 v[34:37], v11 offset:58944
	ds_read_b128 v[56:59], v11 offset:58960
	ds_read_b128 v[74:77], v11 offset:58976
	ds_read_b128 v[78:81], v11 offset:58992
	v_fma_f32 v103, -v30, v32, v103
	v_fma_f32 v33, -v30, v33, v117
	v_fma_f32 v108, -v30, v38, v108
	v_fma_f32 v109, -v30, v39, v109
	s_waitcnt lgkmcnt(10)
	v_fma_f32 v114, -v30, v70, v114
	v_fma_f32 v115, -v30, v71, v115
	v_fma_f32 v117, -v30, v72, v118
	v_fma_f32 v118, -v30, v73, v119
	s_waitcnt lgkmcnt(9)
	v_fma_f32 v32, -v31, v41, v86
	ds_read_b128 v[38:41], v11 offset:59120
	ds_read_b128 v[68:71], v11 offset:59136
	v_fma_f32 v86, -v31, v42, v87
	v_fma_f32 v87, -v31, v43, v88
	s_waitcnt lgkmcnt(10)
	v_fma_f32 v88, -v31, v60, v89
	v_fma_f32 v89, -v31, v61, v90
	v_fma_f32 v90, -v31, v62, v91
	v_fma_f32 v91, -v31, v63, v120
	s_waitcnt lgkmcnt(9)
	v_fma_f32 v84, -v31, v44, v84
	v_fma_f32 v92, -v31, v45, v92
	v_fma_f32 v85, -v31, v46, v85
	v_fma_f32 v93, -v31, v47, v93
	s_waitcnt lgkmcnt(8)
	v_fma_f32 v94, -v31, v48, v94
	v_fma_f32 v95, -v31, v49, v95
	v_fma_f32 v96, -v31, v50, v96
	v_fma_f32 v97, -v31, v51, v97
	s_waitcnt lgkmcnt(7)
	v_fma_f32 v98, -v31, v52, v98
	v_fma_f32 v99, -v31, v53, v99
	ds_read_b128 v[42:45], v11 offset:59152
	ds_read_b128 v[46:49], v11 offset:59168
	ds_read_b128 v[50:53], v11 offset:59184
	ds_read_b128 v[60:63], v11 offset:59200
	v_fma_f32 v100, -v31, v54, v100
	v_fma_f32 v101, -v31, v55, v101
	s_waitcnt lgkmcnt(10)
	v_fma_f32 v102, -v31, v64, v102
	v_fma_f32 v116, -v31, v65, v116
	v_fma_f32 v82, -v31, v66, v82
	v_fma_f32 v83, -v31, v67, v83
	s_waitcnt lgkmcnt(9)
	v_fma_f32 v103, -v31, v34, v103
	v_fma_f32 v119, -v31, v35, v33
	v_fma_f32 v104, -v31, v36, v104
	v_fma_f32 v105, -v31, v37, v105
	s_waitcnt lgkmcnt(8)
	v_fma_f32 v106, -v31, v56, v106
	v_fma_f32 v107, -v31, v57, v107
	v_fma_f32 v58, -v31, v58, v108
	v_fma_f32 v59, -v31, v59, v109
	s_waitcnt lgkmcnt(7)
	v_fma_f32 v108, -v31, v74, v110
	v_fma_f32 v109, -v31, v75, v111
	ds_read_b128 v[34:37], v11 offset:59216
	ds_read_b128 v[54:57], v11 offset:59232
	ds_read_b128 v[64:67], v11 offset:59248
	ds_read_b128 v[72:75], v11 offset:59264
	v_fma_f32 v110, -v31, v76, v112
	v_fma_f32 v111, -v31, v77, v113
	s_waitcnt lgkmcnt(10)
	v_fma_f32 v112, -v31, v78, v114
	v_fma_f32 v113, -v31, v79, v115
	v_fma_f32 v80, -v31, v80, v117
	v_fma_f32 v81, -v31, v81, v118
	s_waitcnt lgkmcnt(9)
	v_fma_f32 v33, -v32, v40, v86
	v_fma_f32 v86, -v32, v41, v87
	ds_read_b128 v[38:41], v11 offset:59392
	ds_read_b128 v[76:79], v11 offset:59408
	s_waitcnt lgkmcnt(1)
	v_fma_f32 v40, -v32, v68, v88
	v_fma_f32 v87, -v32, v69, v89
	v_fma_f32 v88, -v32, v70, v90
	v_fma_f32 v89, -v32, v71, v91
	v_fma_f32 v84, -v32, v42, v84
	v_fma_f32 v90, -v32, v43, v92
	v_fma_f32 v85, -v32, v44, v85
	v_fma_f32 v91, -v32, v45, v93
	v_fma_f32 v92, -v32, v46, v94
	v_fma_f32 v93, -v32, v47, v95
	v_fma_f32 v94, -v32, v48, v96
	v_fma_f32 v95, -v32, v49, v97
	v_fma_f32 v96, -v32, v50, v98
	v_fma_f32 v97, -v32, v51, v99
	v_fma_f32 v98, -v32, v52, v100
	v_fma_f32 v99, -v32, v53, v101
	ds_read_b128 v[42:45], v11 offset:59424
	ds_read_b128 v[46:49], v11 offset:59440
	ds_read_b128 v[50:53], v11 offset:59456
	ds_read_b128 v[68:71], v11 offset:59472
	v_fma_f32 v100, -v32, v60, v102
	v_fma_f32 v101, -v32, v61, v116
	v_fma_f32 v82, -v32, v62, v82
	v_fma_f32 v83, -v32, v63, v83
	v_fma_f32 v102, -v32, v34, v103
	v_fma_f32 v103, -v32, v36, v104
	v_fma_f32 v104, -v32, v37, v105
	v_fma_f32 v105, -v32, v54, v106
	v_fma_f32 v106, -v32, v55, v107
	v_fma_f32 v107, -v32, v56, v58
	v_fma_f32 v114, -v32, v57, v59
	v_fma_f32 v108, -v32, v64, v108
	v_fma_f32 v109, -v32, v65, v109
	ds_read_b128 v[36:39], v11 offset:59488
	ds_read_b128 v[54:57], v11 offset:59504
	ds_read_b128 v[58:61], v11 offset:59520
	ds_read_b128 v[62:65], v11 offset:59536
	v_fma_f32 v35, -v32, v35, v119
	v_fma_f32 v66, -v32, v66, v110
	v_fma_f32 v67, -v32, v67, v111
	v_fma_f32 v110, -v32, v72, v112
	v_fma_f32 v111, -v32, v73, v113
	v_fma_f32 v80, -v32, v74, v80
	v_fma_f32 v81, -v32, v75, v81
	ds_read_b128 v[72:75], v11 offset:59680
	v_fma_f32 v34, -v33, v41, v86
	s_waitcnt lgkmcnt(9)
	v_fma_f32 v86, -v33, v76, v40
	v_fma_f32 v87, -v33, v77, v87
	v_fma_f32 v88, -v33, v78, v88
	v_fma_f32 v89, -v33, v79, v89
	s_waitcnt lgkmcnt(8)
	v_fma_f32 v84, -v33, v42, v84
	v_fma_f32 v90, -v33, v43, v90
	v_fma_f32 v85, -v33, v44, v85
	v_fma_f32 v91, -v33, v45, v91
	s_waitcnt lgkmcnt(7)
	v_fma_f32 v92, -v33, v46, v92
	v_fma_f32 v93, -v33, v47, v93
	v_fma_f32 v94, -v33, v48, v94
	v_fma_f32 v95, -v33, v49, v95
	s_waitcnt lgkmcnt(6)
	v_fma_f32 v96, -v33, v50, v96
	v_fma_f32 v97, -v33, v51, v97
	ds_read_b128 v[40:43], v11 offset:59696
	ds_read_b128 v[44:47], v11 offset:59712
	ds_read_b128 v[48:51], v11 offset:59728
	ds_read_b128 v[76:79], v11 offset:59744
	v_fma_f32 v98, -v33, v52, v98
	v_fma_f32 v99, -v33, v53, v99
	s_waitcnt lgkmcnt(9)
	v_fma_f32 v100, -v33, v68, v100
	v_fma_f32 v101, -v33, v69, v101
	v_fma_f32 v82, -v33, v70, v82
	v_fma_f32 v83, -v33, v71, v83
	s_waitcnt lgkmcnt(8)
	v_fma_f32 v102, -v33, v36, v102
	v_fma_f32 v112, -v33, v37, v35
	v_fma_f32 v103, -v33, v38, v103
	v_fma_f32 v104, -v33, v39, v104
	s_waitcnt lgkmcnt(7)
	v_fma_f32 v105, -v33, v54, v105
	v_fma_f32 v106, -v33, v55, v106
	v_fma_f32 v107, -v33, v56, v107
	v_fma_f32 v113, -v33, v57, v114
	s_waitcnt lgkmcnt(6)
	v_fma_f32 v108, -v33, v58, v108
	v_fma_f32 v109, -v33, v59, v109
	v_fma_f32 v114, -v33, v60, v66
	v_fma_f32 v115, -v33, v61, v67
	ds_read_b128 v[36:39], v11 offset:59760
	ds_read_b128 v[52:55], v11 offset:59776
	ds_read_b128 v[56:59], v11 offset:59792
	ds_read_b128 v[66:69], v11 offset:59808
	s_waitcnt lgkmcnt(9)
	v_fma_f32 v110, -v33, v62, v110
	v_fma_f32 v111, -v33, v63, v111
	v_fma_f32 v64, -v33, v64, v80
	v_fma_f32 v65, -v33, v65, v81
	ds_read_b128 v[60:63], v11 offset:59952
	s_waitcnt lgkmcnt(9)
	v_fma_f32 v35, -v34, v72, v86
	s_waitcnt lgkmcnt(0)
	v_fma_f32 v60, -v34, v73, v87
	v_fma_f32 v86, -v34, v74, v88
	v_fma_f32 v87, -v34, v75, v89
	v_fma_f32 v84, -v34, v40, v84
	v_fma_f32 v88, -v34, v41, v90
	v_fma_f32 v85, -v34, v42, v85
	v_fma_f32 v89, -v34, v43, v91
	v_fma_f32 v90, -v34, v44, v92
	v_fma_f32 v91, -v34, v45, v93
	v_fma_f32 v92, -v34, v46, v94
	v_fma_f32 v93, -v34, v47, v95
	v_fma_f32 v94, -v34, v48, v96
	v_fma_f32 v95, -v34, v49, v97
	v_fma_f32 v96, -v34, v50, v98
	v_fma_f32 v97, -v34, v51, v99
	ds_read_b128 v[40:43], v11 offset:59968
	ds_read_b128 v[44:47], v11 offset:59984
	ds_read_b128 v[48:51], v11 offset:60000
	ds_read_b128 v[70:73], v11 offset:60016
	v_fma_f32 v98, -v34, v76, v100
	v_fma_f32 v99, -v34, v77, v101
	v_fma_f32 v82, -v34, v78, v82
	v_fma_f32 v83, -v34, v79, v83
	v_fma_f32 v100, -v34, v36, v102
	v_fma_f32 v101, -v34, v37, v112
	v_fma_f32 v102, -v34, v38, v103
	v_fma_f32 v103, -v34, v39, v104
	v_fma_f32 v104, -v34, v52, v105
	v_fma_f32 v105, -v34, v53, v106
	v_fma_f32 v106, -v34, v54, v107
	v_fma_f32 v107, -v34, v55, v113
	v_fma_f32 v108, -v34, v56, v108
	v_fma_f32 v109, -v34, v57, v109
	v_fma_f32 v112, -v34, v58, v114
	v_fma_f32 v113, -v34, v59, v115
	ds_read_b128 v[52:55], v11 offset:60032
	ds_read_b128 v[56:59], v11 offset:60048
	ds_read_b128 v[74:77], v11 offset:60064
	ds_read_b128 v[78:81], v11 offset:60080
	v_fma_f32 v110, -v34, v66, v110
	v_fma_f32 v111, -v34, v67, v111
	v_fma_f32 v114, -v34, v68, v64
	v_fma_f32 v115, -v34, v69, v65
	ds_read_b128 v[36:39], v11 offset:60224
	s_waitcnt lgkmcnt(0)
	v_fma_f32 v36, -v35, v61, v60
	v_fma_f32 v37, -v35, v62, v86
	v_fma_f32 v86, -v35, v63, v87
	v_fma_f32 v84, -v35, v40, v84
	v_fma_f32 v87, -v35, v41, v88
	v_fma_f32 v85, -v35, v42, v85
	v_fma_f32 v88, -v35, v43, v89
	v_fma_f32 v89, -v35, v44, v90
	v_fma_f32 v90, -v35, v45, v91
	v_fma_f32 v91, -v35, v46, v92
	v_fma_f32 v92, -v35, v47, v93
	v_fma_f32 v93, -v35, v48, v94
	v_fma_f32 v94, -v35, v49, v95
	v_fma_f32 v95, -v35, v50, v96
	v_fma_f32 v96, -v35, v51, v97
	ds_read_b128 v[40:43], v11 offset:60240
	ds_read_b128 v[44:47], v11 offset:60256
	ds_read_b128 v[48:51], v11 offset:60272
	ds_read_b128 v[60:63], v11 offset:60288
	v_fma_f32 v97, -v35, v70, v98
	v_fma_f32 v98, -v35, v71, v99
	v_fma_f32 v82, -v35, v72, v82
	v_fma_f32 v83, -v35, v73, v83
	v_fma_f32 v99, -v35, v52, v100
	v_fma_f32 v100, -v35, v53, v101
	v_fma_f32 v101, -v35, v54, v102
	v_fma_f32 v102, -v35, v55, v103
	v_fma_f32 v103, -v35, v56, v104
	v_fma_f32 v104, -v35, v57, v105
	v_fma_f32 v105, -v35, v58, v106
	v_fma_f32 v106, -v35, v59, v107
	ds_read_b128 v[52:55], v11 offset:60304
	ds_read_b128 v[56:59], v11 offset:60320
	ds_read_b128 v[64:67], v11 offset:60336
	ds_read_b128 v[68:71], v11 offset:60352
	v_fma_f32 v107, -v35, v74, v108
	v_fma_f32 v108, -v35, v75, v109
	v_fma_f32 v109, -v35, v76, v112
	v_fma_f32 v112, -v35, v77, v113
	v_fma_f32 v110, -v35, v78, v110
	v_fma_f32 v111, -v35, v79, v111
	v_fma_f32 v80, -v35, v80, v114
	v_fma_f32 v81, -v35, v81, v115
	ds_read_b128 v[72:75], v11 offset:60496
	v_fma_f32 v37, -v36, v38, v37
	v_fma_f32 v38, -v36, v39, v86
	s_waitcnt lgkmcnt(8)
	v_fma_f32 v39, -v36, v40, v84
	s_waitcnt lgkmcnt(0)
	v_fma_f32 v72, -v36, v41, v87
	v_fma_f32 v73, -v36, v42, v85
	v_fma_f32 v74, -v36, v43, v88
	v_fma_f32 v84, -v36, v44, v89
	v_fma_f32 v85, -v36, v45, v90
	v_fma_f32 v86, -v36, v46, v91
	v_fma_f32 v87, -v36, v47, v92
	v_fma_f32 v88, -v36, v48, v93
	v_fma_f32 v89, -v36, v49, v94
	v_fma_f32 v90, -v36, v50, v95
	v_fma_f32 v91, -v36, v51, v96
	ds_read_b128 v[40:43], v11 offset:60512
	ds_read_b128 v[44:47], v11 offset:60528
	ds_read_b128 v[48:51], v11 offset:60544
	ds_read_b128 v[76:79], v11 offset:60560
	v_fma_f32 v92, -v36, v60, v97
	v_fma_f32 v93, -v36, v61, v98
	v_fma_f32 v82, -v36, v62, v82
	v_fma_f32 v83, -v36, v63, v83
	v_fma_f32 v94, -v36, v52, v99
	v_fma_f32 v95, -v36, v53, v100
	v_fma_f32 v96, -v36, v54, v101
	v_fma_f32 v97, -v36, v55, v102
	v_fma_f32 v98, -v36, v56, v103
	v_fma_f32 v99, -v36, v57, v104
	v_fma_f32 v100, -v36, v58, v105
	v_fma_f32 v101, -v36, v59, v106
	v_fma_f32 v102, -v36, v64, v107
	v_fma_f32 v103, -v36, v65, v108
	v_fma_f32 v104, -v36, v66, v109
	v_fma_f32 v105, -v36, v67, v112
	ds_read_b128 v[52:55], v11 offset:60576
	ds_read_b128 v[56:59], v11 offset:60592
	ds_read_b128 v[60:63], v11 offset:60608
	ds_read_b128 v[64:67], v11 offset:60624
	v_fma_f32 v106, -v36, v68, v110
	v_fma_f32 v107, -v36, v69, v111
	v_fma_f32 v80, -v36, v70, v80
	v_fma_f32 v81, -v36, v71, v81
	v_fma_f32 v38, -v37, v75, v38
	s_waitcnt lgkmcnt(7)
	v_fma_f32 v39, -v37, v40, v39
	v_fma_f32 v108, -v37, v41, v72
	v_fma_f32 v109, -v37, v42, v73
	v_fma_f32 v110, -v37, v43, v74
	s_waitcnt lgkmcnt(6)
	v_fma_f32 v84, -v37, v44, v84
	v_fma_f32 v85, -v37, v45, v85
	v_fma_f32 v86, -v37, v46, v86
	v_fma_f32 v87, -v37, v47, v87
	s_waitcnt lgkmcnt(5)
	v_fma_f32 v88, -v37, v48, v88
	v_fma_f32 v89, -v37, v49, v89
	v_fma_f32 v90, -v37, v50, v90
	v_fma_f32 v91, -v37, v51, v91
	ds_read_b128 v[40:43], v11 offset:60784
	ds_read_b128 v[44:47], v11 offset:60800
	ds_read_b128 v[48:51], v11 offset:60816
	ds_read_b128 v[68:71], v11 offset:60832
	s_waitcnt lgkmcnt(8)
	v_fma_f32 v76, -v37, v76, v92
	v_fma_f32 v77, -v37, v77, v93
	v_fma_f32 v78, -v37, v78, v82
	v_fma_f32 v79, -v37, v79, v83
	s_waitcnt lgkmcnt(7)
	v_fma_f32 v82, -v37, v52, v94
	v_fma_f32 v83, -v37, v53, v95
	v_fma_f32 v92, -v37, v54, v96
	v_fma_f32 v93, -v37, v55, v97
	s_waitcnt lgkmcnt(6)
	v_fma_f32 v94, -v37, v56, v98
	v_fma_f32 v95, -v37, v57, v99
	v_fma_f32 v96, -v37, v58, v100
	v_fma_f32 v97, -v37, v59, v101
	s_waitcnt lgkmcnt(5)
	v_fma_f32 v98, -v37, v60, v102
	v_fma_f32 v99, -v37, v61, v103
	v_fma_f32 v100, -v37, v62, v104
	v_fma_f32 v101, -v37, v63, v105
	ds_read_b128 v[52:55], v11 offset:60848
	ds_read_b128 v[56:59], v11 offset:60864
	ds_read_b128 v[60:63], v11 offset:60880
	ds_read_b128 v[72:75], v11 offset:60896
	s_waitcnt lgkmcnt(8)
	v_fma_f32 v102, -v37, v64, v106
	v_fma_f32 v103, -v37, v65, v107
	v_fma_f32 v80, -v37, v66, v80
	v_fma_f32 v81, -v37, v67, v81
	s_waitcnt lgkmcnt(7)
	v_fma_f32 v39, -v38, v40, v39
	v_fma_f32 v104, -v38, v41, v108
	v_fma_f32 v105, -v38, v42, v109
	v_fma_f32 v106, -v38, v43, v110
	s_waitcnt lgkmcnt(6)
	v_fma_f32 v84, -v38, v44, v84
	v_fma_f32 v85, -v38, v45, v85
	v_fma_f32 v86, -v38, v46, v86
	v_fma_f32 v87, -v38, v47, v87
	s_waitcnt lgkmcnt(5)
	v_fma_f32 v88, -v38, v48, v88
	v_fma_f32 v89, -v38, v49, v89
	v_fma_f32 v90, -v38, v50, v90
	v_fma_f32 v91, -v38, v51, v91
	ds_read_b128 v[40:43], v11 offset:61056
	ds_read_b128 v[44:47], v11 offset:61072
	ds_read_b128 v[48:51], v11 offset:61088
	ds_read_b128 v[64:67], v11 offset:61104
	s_waitcnt lgkmcnt(8)
	v_fma_f32 v107, -v38, v68, v76
	v_fma_f32 v108, -v38, v69, v77
	v_fma_f32 v109, -v38, v70, v78
	v_fma_f32 v110, -v38, v71, v79
	s_waitcnt lgkmcnt(7)
	v_fma_f32 v82, -v38, v52, v82
	v_fma_f32 v83, -v38, v53, v83
	v_fma_f32 v92, -v38, v54, v92
	v_fma_f32 v93, -v38, v55, v93
	s_waitcnt lgkmcnt(6)
	v_fma_f32 v94, -v38, v56, v94
	v_fma_f32 v95, -v38, v57, v95
	v_fma_f32 v96, -v38, v58, v96
	v_fma_f32 v97, -v38, v59, v97
	s_waitcnt lgkmcnt(5)
	v_fma_f32 v98, -v38, v60, v98
	v_fma_f32 v99, -v38, v61, v99
	v_fma_f32 v100, -v38, v62, v100
	v_fma_f32 v101, -v38, v63, v101
	ds_read_b128 v[52:55], v11 offset:61120
	ds_read_b128 v[56:59], v11 offset:61136
	ds_read_b128 v[60:63], v11 offset:61152
	ds_read_b128 v[68:71], v11 offset:61168
	s_waitcnt lgkmcnt(8)
	v_fma_f32 v102, -v38, v72, v102
	v_fma_f32 v103, -v38, v73, v103
	v_fma_f32 v80, -v38, v74, v80
	v_fma_f32 v81, -v38, v75, v81
	s_waitcnt lgkmcnt(7)
	v_fma_f32 v40, -v39, v41, v104
	v_fma_f32 v41, -v39, v42, v105
	v_fma_f32 v104, -v39, v43, v106
	s_waitcnt lgkmcnt(6)
	v_fma_f32 v84, -v39, v44, v84
	v_fma_f32 v85, -v39, v45, v85
	v_fma_f32 v86, -v39, v46, v86
	v_fma_f32 v87, -v39, v47, v87
	s_waitcnt lgkmcnt(5)
	v_fma_f32 v88, -v39, v48, v88
	v_fma_f32 v89, -v39, v49, v89
	ds_read_b128 v[42:45], v11 offset:61328
	ds_read_b128 v[46:49], v11 offset:61344
	ds_read_b128 v[72:75], v11 offset:61360
	ds_read_b128 v[76:79], v11 offset:61376
	v_fma_f32 v90, -v39, v50, v90
	v_fma_f32 v91, -v39, v51, v91
	s_waitcnt lgkmcnt(8)
	v_fma_f32 v105, -v39, v64, v107
	v_fma_f32 v106, -v39, v65, v108
	v_fma_f32 v107, -v39, v66, v109
	v_fma_f32 v108, -v39, v67, v110
	s_waitcnt lgkmcnt(7)
	v_fma_f32 v82, -v39, v52, v82
	v_fma_f32 v83, -v39, v53, v83
	v_fma_f32 v92, -v39, v54, v92
	v_fma_f32 v93, -v39, v55, v93
	s_waitcnt lgkmcnt(6)
	v_fma_f32 v94, -v39, v56, v94
	v_fma_f32 v95, -v39, v57, v95
	v_fma_f32 v96, -v39, v58, v96
	v_fma_f32 v97, -v39, v59, v97
	s_waitcnt lgkmcnt(5)
	v_fma_f32 v98, -v39, v60, v98
	v_fma_f32 v99, -v39, v61, v99
	v_fma_f32 v100, -v39, v62, v100
	v_fma_f32 v101, -v39, v63, v101
	ds_read_b128 v[50:53], v11 offset:61392
	ds_read_b128 v[54:57], v11 offset:61408
	ds_read_b128 v[58:61], v11 offset:61424
	ds_read_b128 v[62:65], v11 offset:61440
	s_waitcnt lgkmcnt(8)
	v_fma_f32 v102, -v39, v68, v102
	v_fma_f32 v103, -v39, v69, v103
	v_fma_f32 v80, -v39, v70, v80
	v_fma_f32 v81, -v39, v71, v81
	s_waitcnt lgkmcnt(7)
	v_fma_f32 v41, -v40, v44, v41
	v_fma_f32 v104, -v40, v45, v104
	s_waitcnt lgkmcnt(6)
	v_fma_f32 v84, -v40, v46, v84
	v_fma_f32 v85, -v40, v47, v85
	v_fma_f32 v86, -v40, v48, v86
	v_fma_f32 v87, -v40, v49, v87
	s_waitcnt lgkmcnt(5)
	v_fma_f32 v88, -v40, v72, v88
	v_fma_f32 v89, -v40, v73, v89
	ds_read_b128 v[42:45], v11 offset:61600
	ds_read_b128 v[46:49], v11 offset:61616
	ds_read_b128 v[66:69], v11 offset:61632
	ds_read_b128 v[70:73], v11 offset:61648
	v_fma_f32 v90, -v40, v74, v90
	v_fma_f32 v91, -v40, v75, v91
	s_waitcnt lgkmcnt(3)
	v_fma_f32 v43, -v40, v76, v105
	v_fma_f32 v105, -v40, v77, v106
	v_fma_f32 v78, -v40, v78, v107
	v_fma_f32 v79, -v40, v79, v108
	v_fma_f32 v82, -v40, v50, v82
	v_fma_f32 v83, -v40, v51, v83
	v_fma_f32 v92, -v40, v52, v92
	v_fma_f32 v93, -v40, v53, v93
	v_fma_f32 v94, -v40, v54, v94
	v_fma_f32 v95, -v40, v55, v95
	v_fma_f32 v96, -v40, v56, v96
	v_fma_f32 v97, -v40, v57, v97
	v_fma_f32 v98, -v40, v58, v98
	v_fma_f32 v99, -v40, v59, v99
	v_fma_f32 v100, -v40, v60, v100
	v_fma_f32 v101, -v40, v61, v101
	ds_read_b128 v[50:53], v11 offset:61664
	ds_read_b128 v[54:57], v11 offset:61680
	ds_read_b128 v[58:61], v11 offset:61696
	ds_read_b128 v[74:77], v11 offset:61712
	v_fma_f32 v102, -v40, v62, v102
	v_fma_f32 v103, -v40, v63, v103
	v_fma_f32 v80, -v40, v64, v80
	v_fma_f32 v81, -v40, v65, v81
	v_fma_f32 v42, -v41, v45, v104
	s_waitcnt lgkmcnt(6)
	v_fma_f32 v84, -v41, v46, v84
	v_fma_f32 v85, -v41, v47, v85
	s_waitcnt lgkmcnt(5)
	v_fma_f32 v88, -v41, v66, v88
	v_fma_f32 v89, -v41, v67, v89
	v_fma_f32 v90, -v41, v68, v90
	v_fma_f32 v91, -v41, v69, v91
	ds_read_b128 v[44:47], v11 offset:61888
	ds_read_b128 v[62:65], v11 offset:61904
	ds_read_b128 v[66:69], v11 offset:61920
	v_fma_f32 v86, -v41, v48, v86
	v_fma_f32 v87, -v41, v49, v87
	s_waitcnt lgkmcnt(7)
	v_fma_f32 v104, -v41, v70, v43
	v_fma_f32 v105, -v41, v71, v105
	v_fma_f32 v78, -v41, v72, v78
	v_fma_f32 v79, -v41, v73, v79
	s_waitcnt lgkmcnt(6)
	v_fma_f32 v82, -v41, v50, v82
	v_fma_f32 v83, -v41, v51, v83
	v_fma_f32 v92, -v41, v52, v92
	v_fma_f32 v93, -v41, v53, v93
	s_waitcnt lgkmcnt(5)
	v_fma_f32 v94, -v41, v54, v94
	v_fma_f32 v95, -v41, v55, v95
	v_fma_f32 v96, -v41, v56, v96
	v_fma_f32 v97, -v41, v57, v97
	s_waitcnt lgkmcnt(4)
	v_fma_f32 v98, -v41, v58, v98
	v_fma_f32 v99, -v41, v59, v99
	ds_read_b128 v[48:51], v11 offset:61936
	ds_read_b128 v[52:55], v11 offset:61952
	ds_read_b128 v[56:59], v11 offset:61968
	ds_read_b128 v[70:73], v11 offset:61984
	v_fma_f32 v100, -v41, v60, v100
	v_fma_f32 v101, -v41, v61, v101
	s_waitcnt lgkmcnt(7)
	v_fma_f32 v102, -v41, v74, v102
	v_fma_f32 v103, -v41, v75, v103
	v_fma_f32 v80, -v41, v76, v80
	v_fma_f32 v81, -v41, v77, v81
	s_waitcnt lgkmcnt(6)
	v_fma_f32 v43, -v42, v44, v84
	v_fma_f32 v84, -v42, v45, v85
	v_fma_f32 v85, -v42, v46, v86
	v_fma_f32 v86, -v42, v47, v87
	s_waitcnt lgkmcnt(5)
	v_fma_f32 v87, -v42, v62, v88
	v_fma_f32 v88, -v42, v63, v89
	ds_read_b128 v[44:47], v11 offset:62160
	ds_read_b128 v[60:63], v11 offset:62176
	ds_read_b128 v[74:77], v11 offset:62192
	v_fma_f32 v89, -v42, v64, v90
	v_fma_f32 v90, -v42, v65, v91
	s_waitcnt lgkmcnt(7)
	v_fma_f32 v91, -v42, v66, v104
	v_fma_f32 v104, -v42, v67, v105
	v_fma_f32 v105, -v42, v68, v78
	v_fma_f32 v106, -v42, v69, v79
	s_waitcnt lgkmcnt(6)
	v_fma_f32 v82, -v42, v48, v82
	v_fma_f32 v83, -v42, v49, v83
	v_fma_f32 v92, -v42, v50, v92
	v_fma_f32 v93, -v42, v51, v93
	s_waitcnt lgkmcnt(5)
	v_fma_f32 v94, -v42, v52, v94
	v_fma_f32 v95, -v42, v53, v95
	v_fma_f32 v96, -v42, v54, v96
	v_fma_f32 v97, -v42, v55, v97
	s_waitcnt lgkmcnt(4)
	v_fma_f32 v98, -v42, v56, v98
	v_fma_f32 v99, -v42, v57, v99
	v_fma_f32 v100, -v42, v58, v100
	v_fma_f32 v101, -v42, v59, v101
	ds_read_b128 v[48:51], v11 offset:62208
	ds_read_b128 v[52:55], v11 offset:62224
	ds_read_b128 v[56:59], v11 offset:62240
	ds_read_b128 v[64:67], v11 offset:62256
	s_waitcnt lgkmcnt(7)
	v_fma_f32 v102, -v42, v70, v102
	v_fma_f32 v103, -v42, v71, v103
	v_fma_f32 v72, -v42, v72, v80
	v_fma_f32 v73, -v42, v73, v81
	s_waitcnt lgkmcnt(6)
	v_fma_f32 v44, -v43, v45, v84
	v_fma_f32 v45, -v43, v46, v85
	v_fma_f32 v84, -v43, v47, v86
	s_waitcnt lgkmcnt(5)
	v_fma_f32 v85, -v43, v60, v87
	v_fma_f32 v86, -v43, v61, v88
	v_fma_f32 v87, -v43, v62, v89
	v_fma_f32 v88, -v43, v63, v90
	ds_read_b128 v[60:63], v11 offset:62432
	ds_read_b128 v[68:71], v11 offset:62448
	ds_read_b128 v[78:81], v11 offset:62464
	s_waitcnt lgkmcnt(7)
	v_fma_f32 v74, -v43, v74, v91
	v_fma_f32 v75, -v43, v75, v104
	v_fma_f32 v76, -v43, v76, v105
	v_fma_f32 v77, -v43, v77, v106
	s_waitcnt lgkmcnt(6)
	v_fma_f32 v82, -v43, v48, v82
	v_fma_f32 v83, -v43, v49, v83
	v_fma_f32 v89, -v43, v50, v92
	v_fma_f32 v90, -v43, v51, v93
	s_waitcnt lgkmcnt(5)
	v_fma_f32 v91, -v43, v52, v94
	v_fma_f32 v92, -v43, v53, v95
	v_fma_f32 v93, -v43, v54, v96
	v_fma_f32 v94, -v43, v55, v97
	s_waitcnt lgkmcnt(4)
	v_fma_f32 v95, -v43, v56, v98
	v_fma_f32 v96, -v43, v57, v99
	v_fma_f32 v97, -v43, v58, v100
	v_fma_f32 v98, -v43, v59, v101
	ds_read_b128 v[46:49], v11 offset:62480
	ds_read_b128 v[50:53], v11 offset:62496
	ds_read_b128 v[54:57], v11 offset:62512
	s_waitcnt lgkmcnt(5)
	ds_read_b128 v[58:61], v11 offset:62528
	v_fma_f32 v99, -v43, v64, v102
	v_fma_f32 v100, -v43, v65, v103
	v_fma_f32 v101, -v43, v66, v72
	v_fma_f32 v102, -v43, v67, v73
	v_fma_f32 v45, -v44, v62, v45
	v_fma_f32 v84, -v44, v63, v84
	s_waitcnt lgkmcnt(5)
	v_fma_f32 v85, -v44, v68, v85
	v_fma_f32 v86, -v44, v69, v86
	v_fma_f32 v87, -v44, v70, v87
	v_fma_f32 v88, -v44, v71, v88
	ds_read_b128 v[62:65], v11 offset:62704
	ds_read_b128 v[66:69], v11 offset:62720
	ds_read_b128 v[70:73], v11 offset:62736
	s_waitcnt lgkmcnt(2)
	v_fma_f32 v64, -v44, v78, v74
	v_fma_f32 v103, -v44, v79, v75
	v_fma_f32 v104, -v44, v80, v76
	v_fma_f32 v105, -v44, v81, v77
	v_fma_f32 v47, -v44, v47, v83
	v_fma_f32 v83, -v44, v48, v89
	v_fma_f32 v89, -v44, v49, v90
	v_fma_f32 v90, -v44, v50, v91
	v_fma_f32 v91, -v44, v51, v92
	v_fma_f32 v92, -v44, v52, v93
	v_fma_f32 v93, -v44, v53, v94
	v_fma_f32 v94, -v44, v54, v95
	v_fma_f32 v95, -v44, v55, v96
	ds_read_b128 v[48:51], v11 offset:62752
	ds_read_b128 v[52:55], v11 offset:62768
	ds_read_b128 v[74:77], v11 offset:62784
	ds_read_b128 v[78:81], v11 offset:62800
	v_fma_f32 v82, -v44, v46, v82
	v_fma_f32 v96, -v44, v56, v97
	v_fma_f32 v97, -v44, v57, v98
	v_fma_f32 v98, -v44, v58, v99
	v_fma_f32 v99, -v44, v59, v100
	v_fma_f32 v100, -v44, v60, v101
	v_fma_f32 v101, -v44, v61, v102
	ds_read_b128 v[56:59], v11 offset:62992
	ds_read_b128 v[60:63], v11 offset:63008
	v_fma_f32 v46, -v45, v65, v84
	s_waitcnt lgkmcnt(7)
	v_fma_f32 v84, -v45, v66, v85
	v_fma_f32 v85, -v45, v67, v86
	v_fma_f32 v86, -v45, v68, v87
	v_fma_f32 v87, -v45, v69, v88
	s_waitcnt lgkmcnt(6)
	v_fma_f32 v88, -v45, v70, v64
	v_fma_f32 v102, -v45, v71, v103
	v_fma_f32 v103, -v45, v72, v104
	v_fma_f32 v104, -v45, v73, v105
	s_waitcnt lgkmcnt(5)
	v_fma_f32 v82, -v45, v48, v82
	v_fma_f32 v105, -v45, v49, v47
	v_fma_f32 v83, -v45, v50, v83
	v_fma_f32 v89, -v45, v51, v89
	s_waitcnt lgkmcnt(4)
	v_fma_f32 v90, -v45, v52, v90
	v_fma_f32 v91, -v45, v53, v91
	v_fma_f32 v92, -v45, v54, v92
	v_fma_f32 v93, -v45, v55, v93
	ds_read_b128 v[48:51], v11 offset:63024
	ds_read_b128 v[52:55], v11 offset:63040
	ds_read_b128 v[64:67], v11 offset:63056
	ds_read_b128 v[68:71], v11 offset:63072
	s_waitcnt lgkmcnt(7)
	v_fma_f32 v94, -v45, v74, v94
	v_fma_f32 v95, -v45, v75, v95
	v_fma_f32 v76, -v45, v76, v96
	v_fma_f32 v77, -v45, v77, v97
	s_waitcnt lgkmcnt(6)
	v_fma_f32 v96, -v45, v78, v98
	v_fma_f32 v97, -v45, v79, v99
	v_fma_f32 v80, -v45, v80, v100
	v_fma_f32 v81, -v45, v81, v101
	s_waitcnt lgkmcnt(5)
	v_fma_f32 v47, -v46, v56, v84
	v_fma_f32 v84, -v46, v57, v85
	v_fma_f32 v85, -v46, v58, v86
	v_fma_f32 v86, -v46, v59, v87
	ds_read_b128 v[56:59], v11 offset:63264
	ds_read_b128 v[72:75], v11 offset:63280
	s_waitcnt lgkmcnt(6)
	v_fma_f32 v87, -v46, v60, v88
	v_fma_f32 v88, -v46, v61, v102
	v_fma_f32 v98, -v46, v62, v103
	v_fma_f32 v99, -v46, v63, v104
	s_waitcnt lgkmcnt(5)
	v_fma_f32 v83, -v46, v50, v83
	v_fma_f32 v89, -v46, v51, v89
	s_waitcnt lgkmcnt(4)
	v_fma_f32 v90, -v46, v52, v90
	v_fma_f32 v91, -v46, v53, v91
	s_waitcnt lgkmcnt(3)
	v_fma_f32 v94, -v46, v64, v94
	v_fma_f32 v95, -v46, v65, v95
	v_fma_f32 v100, -v46, v66, v76
	v_fma_f32 v101, -v46, v67, v77
	ds_read_b128 v[50:53], v11 offset:63296
	ds_read_b128 v[60:63], v11 offset:63312
	ds_read_b128 v[64:67], v11 offset:63328
	ds_read_b128 v[76:79], v11 offset:63344
	v_fma_f32 v82, -v46, v48, v82
	v_fma_f32 v49, -v46, v49, v105
	v_fma_f32 v92, -v46, v54, v92
	v_fma_f32 v93, -v46, v55, v93
	s_waitcnt lgkmcnt(6)
	v_fma_f32 v96, -v46, v68, v96
	v_fma_f32 v97, -v46, v69, v97
	v_fma_f32 v80, -v46, v70, v80
	v_fma_f32 v81, -v46, v71, v81
	s_waitcnt lgkmcnt(5)
	v_fma_f32 v48, -v47, v57, v84
	ds_read_b128 v[54:57], v11 offset:63536
	ds_read_b128 v[68:71], v11 offset:63552
	v_fma_f32 v84, -v47, v58, v85
	v_fma_f32 v85, -v47, v59, v86
	s_waitcnt lgkmcnt(6)
	v_fma_f32 v86, -v47, v72, v87
	v_fma_f32 v87, -v47, v73, v88
	v_fma_f32 v88, -v47, v74, v98
	v_fma_f32 v98, -v47, v75, v99
	s_waitcnt lgkmcnt(5)
	v_fma_f32 v82, -v47, v50, v82
	v_fma_f32 v99, -v47, v51, v49
	v_fma_f32 v83, -v47, v52, v83
	v_fma_f32 v89, -v47, v53, v89
	s_waitcnt lgkmcnt(4)
	v_fma_f32 v90, -v47, v60, v90
	v_fma_f32 v91, -v47, v61, v91
	v_fma_f32 v92, -v47, v62, v92
	v_fma_f32 v93, -v47, v63, v93
	s_waitcnt lgkmcnt(3)
	v_fma_f32 v94, -v47, v64, v94
	v_fma_f32 v95, -v47, v65, v95
	ds_read_b128 v[50:53], v11 offset:63568
	ds_read_b128 v[58:61], v11 offset:63584
	ds_read_b128 v[62:65], v11 offset:63600
	ds_read_b128 v[72:75], v11 offset:63616
	v_fma_f32 v66, -v47, v66, v100
	v_fma_f32 v67, -v47, v67, v101
	s_waitcnt lgkmcnt(6)
	v_fma_f32 v96, -v47, v76, v96
	v_fma_f32 v97, -v47, v77, v97
	v_fma_f32 v80, -v47, v78, v80
	v_fma_f32 v81, -v47, v79, v81
	s_waitcnt lgkmcnt(5)
	v_fma_f32 v49, -v48, v56, v84
	v_fma_f32 v84, -v48, v57, v85
	ds_read_b128 v[54:57], v11 offset:63808
	ds_read_b128 v[76:79], v11 offset:63824
	s_waitcnt lgkmcnt(1)
	v_fma_f32 v56, -v48, v68, v86
	v_fma_f32 v85, -v48, v69, v87
	v_fma_f32 v86, -v48, v70, v88
	v_fma_f32 v87, -v48, v71, v98
	v_fma_f32 v83, -v48, v52, v83
	v_fma_f32 v88, -v48, v53, v89
	v_fma_f32 v89, -v48, v58, v90
	v_fma_f32 v90, -v48, v59, v91
	v_fma_f32 v91, -v48, v60, v92
	v_fma_f32 v92, -v48, v61, v93
	v_fma_f32 v93, -v48, v62, v94
	v_fma_f32 v94, -v48, v63, v95
	v_fma_f32 v95, -v48, v64, v66
	v_fma_f32 v98, -v48, v65, v67
	ds_read_b128 v[52:55], v11 offset:63840
	ds_read_b128 v[58:61], v11 offset:63856
	ds_read_b128 v[62:65], v11 offset:63872
	ds_read_b128 v[66:69], v11 offset:63888
	v_fma_f32 v82, -v48, v50, v82
	v_fma_f32 v51, -v48, v51, v99
	v_fma_f32 v96, -v48, v72, v96
	v_fma_f32 v97, -v48, v73, v97
	v_fma_f32 v80, -v48, v74, v80
	v_fma_f32 v81, -v48, v75, v81
	ds_read_b128 v[70:73], v11 offset:64096
	v_fma_f32 v50, -v49, v57, v84
	s_waitcnt lgkmcnt(5)
	v_fma_f32 v84, -v49, v76, v56
	v_fma_f32 v85, -v49, v77, v85
	v_fma_f32 v78, -v49, v78, v86
	v_fma_f32 v79, -v49, v79, v87
	s_waitcnt lgkmcnt(4)
	v_fma_f32 v82, -v49, v52, v82
	v_fma_f32 v86, -v49, v53, v51
	v_fma_f32 v83, -v49, v54, v83
	v_fma_f32 v87, -v49, v55, v88
	s_waitcnt lgkmcnt(3)
	v_fma_f32 v88, -v49, v58, v89
	v_fma_f32 v89, -v49, v59, v90
	v_fma_f32 v90, -v49, v60, v91
	v_fma_f32 v91, -v49, v61, v92
	s_waitcnt lgkmcnt(2)
	v_fma_f32 v92, -v49, v62, v93
	v_fma_f32 v93, -v49, v63, v94
	ds_read_b128 v[52:55], v11 offset:64112
	ds_read_b128 v[56:59], v11 offset:64128
	ds_read_b128 v[60:63], v11 offset:64144
	ds_read_b128 v[74:77], v11 offset:64160
	v_fma_f32 v94, -v49, v64, v95
	v_fma_f32 v95, -v49, v65, v98
	s_waitcnt lgkmcnt(5)
	v_fma_f32 v96, -v49, v66, v96
	v_fma_f32 v97, -v49, v67, v97
	v_fma_f32 v98, -v49, v68, v80
	v_fma_f32 v99, -v49, v69, v81
	ds_read_b128 v[64:67], v11 offset:64368
	s_waitcnt lgkmcnt(5)
	v_fma_f32 v51, -v50, v70, v84
	s_waitcnt lgkmcnt(0)
	v_fma_f32 v64, -v50, v71, v85
	v_fma_f32 v84, -v50, v72, v78
	v_fma_f32 v85, -v50, v73, v79
	v_fma_f32 v53, -v50, v53, v86
	v_fma_f32 v83, -v50, v54, v83
	v_fma_f32 v86, -v50, v55, v87
	v_fma_f32 v87, -v50, v56, v88
	v_fma_f32 v88, -v50, v57, v89
	v_fma_f32 v89, -v50, v58, v90
	v_fma_f32 v90, -v50, v59, v91
	v_fma_f32 v91, -v50, v60, v92
	v_fma_f32 v92, -v50, v61, v93
	ds_read_b128 v[54:57], v11 offset:64384
	ds_read_b128 v[58:61], v11 offset:64400
	ds_read_b128 v[68:71], v11 offset:64416
	ds_read_b128 v[78:81], v11 offset:64432
	v_fma_f32 v82, -v50, v52, v82
	v_fma_f32 v62, -v50, v62, v94
	v_fma_f32 v63, -v50, v63, v95
	v_fma_f32 v93, -v50, v74, v96
	v_fma_f32 v94, -v50, v75, v97
	v_fma_f32 v76, -v50, v76, v98
	v_fma_f32 v77, -v50, v77, v99
	ds_read_b128 v[72:75], v11 offset:64640
	v_fma_f32 v52, -v51, v65, v64
	v_fma_f32 v84, -v51, v66, v84
	v_fma_f32 v85, -v51, v67, v85
	s_waitcnt lgkmcnt(4)
	v_fma_f32 v82, -v51, v54, v82
	v_fma_f32 v95, -v51, v55, v53
	v_fma_f32 v83, -v51, v56, v83
	v_fma_f32 v86, -v51, v57, v86
	s_waitcnt lgkmcnt(3)
	v_fma_f32 v87, -v51, v58, v87
	v_fma_f32 v88, -v51, v59, v88
	v_fma_f32 v89, -v51, v60, v89
	v_fma_f32 v90, -v51, v61, v90
	s_waitcnt lgkmcnt(2)
	v_fma_f32 v91, -v51, v68, v91
	v_fma_f32 v92, -v51, v69, v92
	v_fma_f32 v96, -v51, v70, v62
	v_fma_f32 v97, -v51, v71, v63
	ds_read_b128 v[54:57], v11 offset:64656
	ds_read_b128 v[58:61], v11 offset:64672
	ds_read_b128 v[62:65], v11 offset:64688
	ds_read_b128 v[66:69], v11 offset:64704
	s_waitcnt lgkmcnt(5)
	v_fma_f32 v93, -v51, v78, v93
	v_fma_f32 v94, -v51, v79, v94
	v_fma_f32 v98, -v51, v80, v76
	v_fma_f32 v99, -v51, v81, v77
	s_waitcnt lgkmcnt(4)
	ds_read_b128 v[70:73], v11 offset:64912
	v_fma_f32 v53, -v52, v74, v84
	s_waitcnt lgkmcnt(0)
	v_fma_f32 v70, -v52, v75, v85
	v_fma_f32 v71, -v52, v54, v82
	v_fma_f32 v72, -v52, v56, v83
	v_fma_f32 v82, -v52, v57, v86
	v_fma_f32 v83, -v52, v58, v87
	v_fma_f32 v84, -v52, v59, v88
	v_fma_f32 v85, -v52, v60, v89
	v_fma_f32 v86, -v52, v61, v90
	v_fma_f32 v87, -v52, v62, v91
	v_fma_f32 v88, -v52, v63, v92
	ds_read_b128 v[56:59], v11 offset:64928
	ds_read_b128 v[60:63], v11 offset:64944
	ds_read_b128 v[74:77], v11 offset:64960
	ds_read_b128 v[78:81], v11 offset:64976
	v_fma_f32 v55, -v52, v55, v95
	v_fma_f32 v64, -v52, v64, v96
	v_fma_f32 v65, -v52, v65, v97
	v_fma_f32 v89, -v52, v66, v93
	v_fma_f32 v90, -v52, v67, v94
	v_fma_f32 v91, -v52, v68, v98
	v_fma_f32 v92, -v52, v69, v99
	v_fma_f32 v54, -v53, v73, v70
	s_waitcnt lgkmcnt(3)
	v_fma_f32 v73, -v53, v56, v71
	v_fma_f32 v93, -v53, v57, v55
	v_fma_f32 v72, -v53, v58, v72
	v_fma_f32 v82, -v53, v59, v82
	s_waitcnt lgkmcnt(2)
	v_fma_f32 v83, -v53, v60, v83
	v_fma_f32 v84, -v53, v61, v84
	v_fma_f32 v85, -v53, v62, v85
	v_fma_f32 v86, -v53, v63, v86
	s_waitcnt lgkmcnt(1)
	v_fma_f32 v76, -v53, v76, v64
	v_fma_f32 v77, -v53, v77, v65
	ds_read_b128 v[56:59], v11 offset:65200
	ds_read_b128 v[60:63], v11 offset:65216
	ds_read_b128 v[64:67], v11 offset:65232
	ds_read_b128 v[68:71], v11 offset:65248
	v_fma_f32 v74, -v53, v74, v87
	v_fma_f32 v75, -v53, v75, v88
	s_waitcnt lgkmcnt(4)
	v_fma_f32 v78, -v53, v78, v89
	v_fma_f32 v79, -v53, v79, v90
	v_fma_f32 v80, -v53, v80, v91
	v_fma_f32 v81, -v53, v81, v92
	s_waitcnt lgkmcnt(3)
	v_fma_f32 v55, -v54, v56, v73
	v_fma_f32 v87, -v54, v57, v93
	v_fma_f32 v88, -v54, v58, v72
	v_fma_f32 v82, -v54, v59, v82
	s_waitcnt lgkmcnt(2)
	v_fma_f32 v83, -v54, v60, v83
	v_fma_f32 v84, -v54, v61, v84
	v_fma_f32 v85, -v54, v62, v85
	v_fma_f32 v86, -v54, v63, v86
	s_waitcnt lgkmcnt(1)
	v_fma_f32 v89, -v54, v64, v74
	v_fma_f32 v90, -v54, v65, v75
	v_fma_f32 v76, -v54, v66, v76
	v_fma_f32 v77, -v54, v67, v77
	ds_read_b128 v[56:59], v11 offset:65472
	ds_read_b128 v[60:63], v11 offset:65488
	ds_read_b128 v[64:67], v11 offset:65504
	ds_read_b128 v[72:75], v11 offset:65520
	s_waitcnt lgkmcnt(4)
	v_fma_f32 v78, -v54, v68, v78
	v_fma_f32 v79, -v54, v69, v79
	v_fma_f32 v80, -v54, v70, v80
	v_fma_f32 v81, -v54, v71, v81
	s_waitcnt lgkmcnt(3)
	v_fma_f32 v11, -v55, v57, v87
	v_fma_f32 v87, -v55, v58, v88
	v_fma_f32 v82, -v55, v59, v82
	s_waitcnt lgkmcnt(2)
	v_fma_f32 v83, -v55, v60, v83
	v_fma_f32 v84, -v55, v61, v84
	v_fma_f32 v85, -v55, v62, v85
	v_fma_f32 v86, -v55, v63, v86
	s_waitcnt lgkmcnt(1)
	v_fma_f32 v88, -v55, v64, v89
	v_fma_f32 v89, -v55, v65, v90
	v_fma_f32 v76, -v55, v66, v76
	v_fma_f32 v77, -v55, v67, v77
	ds_read_b128 v[56:59], v7 offset:13520
	ds_read_b128 v[60:63], v7 offset:13536
	ds_read_b128 v[64:67], v7 offset:13552
	ds_read_b128 v[68:71], v7 offset:13568
	s_waitcnt lgkmcnt(3)
	v_fma_f32 v57, -v55, v72, v78
	v_fma_f32 v90, -v55, v73, v79
	v_fma_f32 v80, -v55, v74, v80
	v_fma_f32 v81, -v55, v75, v81
	v_fma_f32 v56, -v11, v58, v87
	v_fma_f32 v82, -v11, v59, v82
	s_waitcnt lgkmcnt(2)
	v_fma_f32 v83, -v11, v60, v83
	v_fma_f32 v84, -v11, v61, v84
	v_fma_f32 v85, -v11, v62, v85
	v_fma_f32 v86, -v11, v63, v86
	s_waitcnt lgkmcnt(1)
	v_fma_f32 v87, -v11, v64, v88
	v_fma_f32 v88, -v11, v65, v89
	v_fma_f32 v66, -v11, v66, v76
	v_fma_f32 v67, -v11, v67, v77
	ds_read_b128 v[58:61], v7 offset:13792
	ds_read_b128 v[62:65], v7 offset:13808
	ds_read_b128 v[72:75], v7 offset:13824
	ds_read_b128 v[76:79], v7 offset:13840
	s_waitcnt lgkmcnt(4)
	v_fma_f32 v89, -v11, v68, v57
	v_fma_f32 v90, -v11, v69, v90
	v_fma_f32 v70, -v11, v70, v80
	v_fma_f32 v71, -v11, v71, v81
	s_waitcnt lgkmcnt(3)
	v_fma_f32 v57, -v56, v61, v82
	s_waitcnt lgkmcnt(2)
	v_fma_f32 v80, -v56, v62, v83
	v_fma_f32 v81, -v56, v63, v84
	v_fma_f32 v82, -v56, v64, v85
	v_fma_f32 v83, -v56, v65, v86
	s_waitcnt lgkmcnt(1)
	v_fma_f32 v74, -v56, v74, v66
	v_fma_f32 v75, -v56, v75, v67
	ds_read_b128 v[58:61], v7 offset:14080
	ds_read_b128 v[62:65], v7 offset:14096
	ds_read_b128 v[66:69], v7 offset:14112
	v_fma_f32 v72, -v56, v72, v87
	v_fma_f32 v73, -v56, v73, v88
	s_waitcnt lgkmcnt(3)
	v_fma_f32 v84, -v56, v76, v89
	v_fma_f32 v85, -v56, v77, v90
	v_fma_f32 v78, -v56, v78, v70
	v_fma_f32 v79, -v56, v79, v71
	s_waitcnt lgkmcnt(2)
	v_fma_f32 v58, -v57, v58, v80
	v_fma_f32 v59, -v57, v59, v81
	v_fma_f32 v80, -v57, v60, v82
	v_fma_f32 v81, -v57, v61, v83
	s_waitcnt lgkmcnt(1)
	v_fma_f32 v82, -v57, v62, v72
	v_fma_f32 v83, -v57, v63, v73
	v_fma_f32 v64, -v57, v64, v74
	v_fma_f32 v65, -v57, v65, v75
	ds_read_b128 v[60:63], v7 offset:14352
	ds_read_b128 v[70:73], v7 offset:14368
	ds_read_b128 v[74:77], v7 offset:14384
	s_waitcnt lgkmcnt(3)
	v_fma_f32 v84, -v57, v66, v84
	v_fma_f32 v85, -v57, v67, v85
	v_fma_f32 v78, -v57, v68, v78
	v_fma_f32 v79, -v57, v69, v79
	s_waitcnt lgkmcnt(2)
	v_fma_f32 v59, -v58, v61, v59
	v_fma_f32 v80, -v58, v62, v80
	v_fma_f32 v81, -v58, v63, v81
	s_waitcnt lgkmcnt(1)
	v_fma_f32 v82, -v58, v70, v82
	v_fma_f32 v83, -v58, v71, v83
	v_fma_f32 v72, -v58, v72, v64
	v_fma_f32 v73, -v58, v73, v65
	ds_read_b128 v[60:63], v7 offset:14624
	ds_read_b128 v[64:67], v7 offset:14640
	ds_read_b128 v[68:71], v7 offset:14656
	s_waitcnt lgkmcnt(2)
	v_fma_f32 v61, -v58, v74, v84
	v_fma_f32 v84, -v58, v75, v85
	v_fma_f32 v85, -v58, v76, v78
	v_fma_f32 v86, -v58, v77, v79
	v_fma_f32 v60, -v59, v62, v80
	v_fma_f32 v80, -v59, v63, v81
	s_waitcnt lgkmcnt(1)
	v_fma_f32 v81, -v59, v64, v82
	v_fma_f32 v82, -v59, v65, v83
	v_fma_f32 v66, -v59, v66, v72
	v_fma_f32 v67, -v59, v67, v73
	ds_read_b128 v[62:65], v7 offset:14896
	ds_read_b128 v[72:75], v7 offset:14912
	ds_read_b128 v[76:79], v7 offset:14928
	s_waitcnt lgkmcnt(3)
	v_fma_f32 v83, -v59, v68, v61
	v_fma_f32 v84, -v59, v69, v84
	v_fma_f32 v70, -v59, v70, v85
	v_fma_f32 v71, -v59, v71, v86
	s_waitcnt lgkmcnt(2)
	v_fma_f32 v61, -v60, v65, v80
	s_waitcnt lgkmcnt(1)
	v_fma_f32 v74, -v60, v74, v66
	v_fma_f32 v75, -v60, v75, v67
	ds_read_b128 v[62:65], v7 offset:15184
	ds_read_b128 v[66:69], v7 offset:15200
	v_fma_f32 v72, -v60, v72, v81
	v_fma_f32 v73, -v60, v73, v82
	s_waitcnt lgkmcnt(2)
	v_fma_f32 v80, -v60, v76, v83
	v_fma_f32 v81, -v60, v77, v84
	v_fma_f32 v78, -v60, v78, v70
	v_fma_f32 v79, -v60, v79, v71
	s_waitcnt lgkmcnt(1)
	v_fma_f32 v62, -v61, v62, v72
	v_fma_f32 v63, -v61, v63, v73
	v_fma_f32 v64, -v61, v64, v74
	v_fma_f32 v65, -v61, v65, v75
	ds_read_b128 v[70:73], v7 offset:15456
	ds_read_b128 v[74:77], v7 offset:15472
	s_waitcnt lgkmcnt(2)
	v_fma_f32 v80, -v61, v66, v80
	v_fma_f32 v81, -v61, v67, v81
	v_fma_f32 v78, -v61, v68, v78
	v_fma_f32 v79, -v61, v69, v79
	s_waitcnt lgkmcnt(1)
	v_fma_f32 v63, -v62, v71, v63
	v_fma_f32 v72, -v62, v72, v64
	v_fma_f32 v73, -v62, v73, v65
	ds_read_b128 v[64:67], v7 offset:15728
	ds_read_b128 v[68:71], v7 offset:15744
	s_waitcnt lgkmcnt(1)
	v_fma_f32 v65, -v62, v74, v80
	v_fma_f32 v80, -v62, v75, v81
	v_fma_f32 v81, -v62, v76, v78
	v_fma_f32 v82, -v62, v77, v79
	v_fma_f32 v64, -v63, v66, v72
	v_fma_f32 v66, -v63, v67, v73
	ds_read_b128 v[72:75], v7 offset:16000
	ds_read_b128 v[76:79], v7 offset:16016
	s_waitcnt lgkmcnt(1)
	v_fma_f32 v72, -v63, v68, v65
	v_fma_f32 v73, -v63, v69, v80
	v_fma_f32 v70, -v63, v70, v81
	v_fma_f32 v71, -v63, v71, v82
	v_fma_f32 v65, -v64, v75, v66
	ds_read_b128 v[66:69], v7 offset:16288
	s_waitcnt lgkmcnt(1)
	v_fma_f32 v74, -v64, v76, v72
	v_fma_f32 v75, -v64, v77, v73
	v_fma_f32 v76, -v64, v78, v70
	v_fma_f32 v77, -v64, v79, v71
	ds_read_b128 v[70:73], v7 offset:16560
	s_waitcnt lgkmcnt(1)
	v_fma_f32 v66, -v65, v66, v74
	v_fma_f32 v67, -v65, v67, v75
	v_fma_f32 v68, -v65, v68, v76
	v_fma_f32 v69, -v65, v69, v77
	ds_read_b128 v[74:77], v7 offset:16832
	s_waitcnt lgkmcnt(1)
	v_fma_f32 v67, -v66, v71, v67
	v_fma_f32 v72, -v66, v72, v68
	v_fma_f32 v73, -v66, v73, v69
	ds_read_b128 v[68:71], v7 offset:17104
	s_waitcnt lgkmcnt(1)
	v_fma_f32 v7, -v67, v76, v72
	s_waitcnt lgkmcnt(0)
	v_fma_f32 v68, -v67, v77, v73
	v_fma_f32 v68, -v7, v71, v68
	v_lshlrev_b32_e32 v69, 2, v2
	v_add_u32_e32 v70, s87, v69
	v_add_u32_e32 v69, s86, v69
	ds_read_b32 v70, v70
	ds_read_b32 v71, v69
	v_lshl_add_u32 v69, v2, 1, s85
	s_waitcnt lgkmcnt(1)
	v_mul_f32_e32 v72, v158, v70
	v_bfe_u32 v73, v72, 16, 1
	s_waitcnt lgkmcnt(0)
	v_mul_f32_e32 v71, v70, v71
	v_add3_u32 v72, v72, v73, s82
	ds_write_b16_d16_hi v69, v72
	v_mul_f32_e32 v72, v158, v71
	v_bfe_u32 v73, v72, 16, 1
	v_add3_u32 v72, v72, v73, s82
	ds_write_b16_d16_hi v69, v72 offset:8704
	v_mul_f32_e32 v72, v6, v70
	v_bfe_u32 v73, v72, 16, 1
	v_add3_u32 v72, v72, v73, s82
	v_mul_f32_e32 v6, v6, v71
	ds_write_b16_d16_hi v69, v72 offset:136
	v_bfe_u32 v72, v6, 16, 1
	v_add3_u32 v6, v6, v72, s82
	ds_write_b16_d16_hi v69, v6 offset:8840
	v_mul_f32_e32 v6, v8, v70
	v_bfe_u32 v72, v6, 16, 1
	v_add3_u32 v6, v6, v72, s82
	ds_write_b16_d16_hi v69, v6 offset:272
	v_mul_f32_e32 v6, v8, v71
	v_bfe_u32 v8, v6, 16, 1
	v_add3_u32 v6, v6, v8, s82
	ds_write_b16_d16_hi v69, v6 offset:8976
	v_mul_f32_e32 v6, v9, v70
	v_bfe_u32 v8, v6, 16, 1
	v_add3_u32 v6, v6, v8, s82
	ds_write_b16_d16_hi v69, v6 offset:408
	v_mul_f32_e32 v6, v9, v71
	v_bfe_u32 v8, v6, 16, 1
	v_add3_u32 v6, v6, v8, s82
	ds_write_b16_d16_hi v69, v6 offset:9112
	v_mul_f32_e32 v6, v10, v70
	v_bfe_u32 v8, v6, 16, 1
	v_add3_u32 v6, v6, v8, s82
	ds_write_b16_d16_hi v69, v6 offset:544
	v_mul_f32_e32 v6, v10, v71
	v_bfe_u32 v8, v6, 16, 1
	v_add3_u32 v6, v6, v8, s82
	ds_write_b16_d16_hi v69, v6 offset:9248
	v_mul_f32_e32 v6, v12, v70
	v_bfe_u32 v8, v6, 16, 1
	v_add3_u32 v6, v6, v8, s82
	ds_write_b16_d16_hi v69, v6 offset:680
	v_mul_f32_e32 v6, v12, v71
	v_bfe_u32 v8, v6, 16, 1
	v_add3_u32 v6, v6, v8, s82
	ds_write_b16_d16_hi v69, v6 offset:9384
	v_mul_f32_e32 v6, v13, v70
	v_bfe_u32 v8, v6, 16, 1
	v_add3_u32 v6, v6, v8, s82
	ds_write_b16_d16_hi v69, v6 offset:816
	v_mul_f32_e32 v6, v13, v71
	v_bfe_u32 v8, v6, 16, 1
	v_add3_u32 v6, v6, v8, s82
	ds_write_b16_d16_hi v69, v6 offset:9520
	v_mul_f32_e32 v6, v14, v70
	v_bfe_u32 v8, v6, 16, 1
	v_add3_u32 v6, v6, v8, s82
	ds_write_b16_d16_hi v69, v6 offset:952
	v_mul_f32_e32 v6, v14, v71
	v_bfe_u32 v8, v6, 16, 1
	v_add3_u32 v6, v6, v8, s82
	ds_write_b16_d16_hi v69, v6 offset:9656
	v_mul_f32_e32 v6, v15, v70
	v_bfe_u32 v8, v6, 16, 1
	v_add3_u32 v6, v6, v8, s82
	ds_write_b16_d16_hi v69, v6 offset:1088
	v_mul_f32_e32 v6, v15, v71
	v_bfe_u32 v8, v6, 16, 1
	v_add3_u32 v6, v6, v8, s82
	ds_write_b16_d16_hi v69, v6 offset:9792
	v_mul_f32_e32 v6, v16, v70
	v_bfe_u32 v8, v6, 16, 1
	v_add3_u32 v6, v6, v8, s82
	ds_write_b16_d16_hi v69, v6 offset:1224
	v_mul_f32_e32 v6, v16, v71
	v_bfe_u32 v8, v6, 16, 1
	v_add3_u32 v6, v6, v8, s82
	ds_write_b16_d16_hi v69, v6 offset:9928
	v_mul_f32_e32 v6, v17, v70
	v_bfe_u32 v8, v6, 16, 1
	v_add3_u32 v6, v6, v8, s82
	ds_write_b16_d16_hi v69, v6 offset:1360
	v_mul_f32_e32 v6, v17, v71
	v_bfe_u32 v8, v6, 16, 1
	v_add3_u32 v6, v6, v8, s82
	ds_write_b16_d16_hi v69, v6 offset:10064
	v_mul_f32_e32 v6, v18, v70
	v_bfe_u32 v8, v6, 16, 1
	v_add3_u32 v6, v6, v8, s82
	ds_write_b16_d16_hi v69, v6 offset:1496
	v_mul_f32_e32 v6, v18, v71
	v_bfe_u32 v8, v6, 16, 1
	v_add3_u32 v6, v6, v8, s82
	ds_write_b16_d16_hi v69, v6 offset:10200
	v_mul_f32_e32 v6, v19, v70
	v_bfe_u32 v8, v6, 16, 1
	v_add3_u32 v6, v6, v8, s82
	ds_write_b16_d16_hi v69, v6 offset:1632
	v_mul_f32_e32 v6, v19, v71
	v_bfe_u32 v8, v6, 16, 1
	v_add3_u32 v6, v6, v8, s82
	ds_write_b16_d16_hi v69, v6 offset:10336
	v_mul_f32_e32 v6, v20, v70
	v_bfe_u32 v8, v6, 16, 1
	v_add3_u32 v6, v6, v8, s82
	ds_write_b16_d16_hi v69, v6 offset:1768
	v_mul_f32_e32 v6, v20, v71
	v_bfe_u32 v8, v6, 16, 1
	v_add3_u32 v6, v6, v8, s82
	ds_write_b16_d16_hi v69, v6 offset:10472
	v_mul_f32_e32 v6, v21, v70
	v_bfe_u32 v8, v6, 16, 1
	v_add3_u32 v6, v6, v8, s82
	ds_write_b16_d16_hi v69, v6 offset:1904
	v_mul_f32_e32 v6, v21, v71
	v_bfe_u32 v8, v6, 16, 1
	v_add3_u32 v6, v6, v8, s82
	ds_write_b16_d16_hi v69, v6 offset:10608
	v_mul_f32_e32 v6, v22, v70
	v_bfe_u32 v8, v6, 16, 1
	v_add3_u32 v6, v6, v8, s82
	ds_write_b16_d16_hi v69, v6 offset:2040
	v_mul_f32_e32 v6, v22, v71
	v_bfe_u32 v8, v6, 16, 1
	v_add3_u32 v6, v6, v8, s82
	ds_write_b16_d16_hi v69, v6 offset:10744
	v_mul_f32_e32 v6, v23, v70
	v_bfe_u32 v8, v6, 16, 1
	v_add3_u32 v6, v6, v8, s82
	ds_write_b16_d16_hi v69, v6 offset:2176
	v_mul_f32_e32 v6, v23, v71
	v_bfe_u32 v8, v6, 16, 1
	v_add3_u32 v6, v6, v8, s82
	ds_write_b16_d16_hi v69, v6 offset:10880
	v_mul_f32_e32 v6, v24, v70
	v_bfe_u32 v8, v6, 16, 1
	v_add3_u32 v6, v6, v8, s82
	ds_write_b16_d16_hi v69, v6 offset:2312
	v_mul_f32_e32 v6, v24, v71
	v_bfe_u32 v8, v6, 16, 1
	v_add3_u32 v6, v6, v8, s82
	ds_write_b16_d16_hi v69, v6 offset:11016
	v_mul_f32_e32 v6, v25, v70
	v_bfe_u32 v8, v6, 16, 1
	v_add3_u32 v6, v6, v8, s82
	ds_write_b16_d16_hi v69, v6 offset:2448
	v_mul_f32_e32 v6, v25, v71
	v_bfe_u32 v8, v6, 16, 1
	v_add3_u32 v6, v6, v8, s82
	ds_write_b16_d16_hi v69, v6 offset:11152
	v_mul_f32_e32 v6, v26, v70
	v_bfe_u32 v8, v6, 16, 1
	v_add3_u32 v6, v6, v8, s82
	ds_write_b16_d16_hi v69, v6 offset:2584
	v_mul_f32_e32 v6, v26, v71
	v_bfe_u32 v8, v6, 16, 1
	v_add3_u32 v6, v6, v8, s82
	ds_write_b16_d16_hi v69, v6 offset:11288
	v_mul_f32_e32 v6, v27, v70
	v_bfe_u32 v8, v6, 16, 1
	v_add3_u32 v6, v6, v8, s82
	ds_write_b16_d16_hi v69, v6 offset:2720
	v_mul_f32_e32 v6, v27, v71
	v_bfe_u32 v8, v6, 16, 1
	v_add3_u32 v6, v6, v8, s82
	ds_write_b16_d16_hi v69, v6 offset:11424
	v_mul_f32_e32 v6, v28, v70
	v_bfe_u32 v8, v6, 16, 1
	v_add3_u32 v6, v6, v8, s82
	ds_write_b16_d16_hi v69, v6 offset:2856
	v_mul_f32_e32 v6, v28, v71
	v_bfe_u32 v8, v6, 16, 1
	v_add3_u32 v6, v6, v8, s82
	ds_write_b16_d16_hi v69, v6 offset:11560
	v_mul_f32_e32 v6, v29, v70
	v_bfe_u32 v8, v6, 16, 1
	v_add3_u32 v6, v6, v8, s82
	ds_write_b16_d16_hi v69, v6 offset:2992
	v_mul_f32_e32 v6, v29, v71
	v_bfe_u32 v8, v6, 16, 1
	v_add3_u32 v6, v6, v8, s82
	ds_write_b16_d16_hi v69, v6 offset:11696
	v_mul_f32_e32 v6, v30, v70
	v_bfe_u32 v8, v6, 16, 1
	v_add3_u32 v6, v6, v8, s82
	ds_write_b16_d16_hi v69, v6 offset:3128
	v_mul_f32_e32 v6, v30, v71
	v_bfe_u32 v8, v6, 16, 1
	v_add3_u32 v6, v6, v8, s82
	ds_write_b16_d16_hi v69, v6 offset:11832
	v_mul_f32_e32 v6, v31, v70
	v_bfe_u32 v8, v6, 16, 1
	v_add3_u32 v6, v6, v8, s82
	ds_write_b16_d16_hi v69, v6 offset:3264
	v_mul_f32_e32 v6, v31, v71
	v_bfe_u32 v8, v6, 16, 1
	v_add3_u32 v6, v6, v8, s82
	ds_write_b16_d16_hi v69, v6 offset:11968
	v_mul_f32_e32 v6, v32, v70
	v_bfe_u32 v8, v6, 16, 1
	v_add3_u32 v6, v6, v8, s82
	ds_write_b16_d16_hi v69, v6 offset:3400
	v_mul_f32_e32 v6, v32, v71
	v_bfe_u32 v8, v6, 16, 1
	v_add3_u32 v6, v6, v8, s82
	ds_write_b16_d16_hi v69, v6 offset:12104
	v_mul_f32_e32 v6, v33, v70
	v_bfe_u32 v8, v6, 16, 1
	v_add3_u32 v6, v6, v8, s82
	ds_write_b16_d16_hi v69, v6 offset:3536
	v_mul_f32_e32 v6, v33, v71
	v_bfe_u32 v8, v6, 16, 1
	v_add3_u32 v6, v6, v8, s82
	ds_write_b16_d16_hi v69, v6 offset:12240
	v_mul_f32_e32 v6, v34, v70
	v_bfe_u32 v8, v6, 16, 1
	v_add3_u32 v6, v6, v8, s82
	ds_write_b16_d16_hi v69, v6 offset:3672
	v_mul_f32_e32 v6, v34, v71
	v_bfe_u32 v8, v6, 16, 1
	v_add3_u32 v6, v6, v8, s82
	ds_write_b16_d16_hi v69, v6 offset:12376
	v_mul_f32_e32 v6, v35, v70
	v_bfe_u32 v8, v6, 16, 1
	v_add3_u32 v6, v6, v8, s82
	ds_write_b16_d16_hi v69, v6 offset:3808
	v_mul_f32_e32 v6, v35, v71
	v_bfe_u32 v8, v6, 16, 1
	v_add3_u32 v6, v6, v8, s82
	ds_write_b16_d16_hi v69, v6 offset:12512
	v_mul_f32_e32 v6, v36, v70
	v_bfe_u32 v8, v6, 16, 1
	v_add3_u32 v6, v6, v8, s82
	ds_write_b16_d16_hi v69, v6 offset:3944
	v_mul_f32_e32 v6, v36, v71
	v_bfe_u32 v8, v6, 16, 1
	v_add3_u32 v6, v6, v8, s82
	ds_write_b16_d16_hi v69, v6 offset:12648
	v_mul_f32_e32 v6, v37, v70
	v_bfe_u32 v8, v6, 16, 1
	v_add3_u32 v6, v6, v8, s82
	ds_write_b16_d16_hi v69, v6 offset:4080
	v_mul_f32_e32 v6, v37, v71
	v_bfe_u32 v8, v6, 16, 1
	v_add3_u32 v6, v6, v8, s82
	ds_write_b16_d16_hi v69, v6 offset:12784
	v_mul_f32_e32 v6, v38, v70
	v_bfe_u32 v8, v6, 16, 1
	v_add3_u32 v6, v6, v8, s82
	ds_write_b16_d16_hi v69, v6 offset:4216
	v_mul_f32_e32 v6, v38, v71
	v_bfe_u32 v8, v6, 16, 1
	v_add3_u32 v6, v6, v8, s82
	ds_write_b16_d16_hi v69, v6 offset:12920
	v_mul_f32_e32 v6, v39, v70
	v_bfe_u32 v8, v6, 16, 1
	v_add3_u32 v6, v6, v8, s82
	ds_write_b16_d16_hi v69, v6 offset:4352
	v_mul_f32_e32 v6, v39, v71
	v_bfe_u32 v8, v6, 16, 1
	v_add3_u32 v6, v6, v8, s82
	ds_write_b16_d16_hi v69, v6 offset:13056
	v_mul_f32_e32 v6, v40, v70
	v_bfe_u32 v8, v6, 16, 1
	v_add3_u32 v6, v6, v8, s82
	ds_write_b16_d16_hi v69, v6 offset:4488
	v_mul_f32_e32 v6, v40, v71
	v_bfe_u32 v8, v6, 16, 1
	v_add3_u32 v6, v6, v8, s82
	ds_write_b16_d16_hi v69, v6 offset:13192
	v_mul_f32_e32 v6, v41, v70
	v_bfe_u32 v8, v6, 16, 1
	v_add3_u32 v6, v6, v8, s82
	ds_write_b16_d16_hi v69, v6 offset:4624
	v_mul_f32_e32 v6, v41, v71
	v_bfe_u32 v8, v6, 16, 1
	v_add3_u32 v6, v6, v8, s82
	ds_write_b16_d16_hi v69, v6 offset:13328
	v_mul_f32_e32 v6, v42, v70
	v_bfe_u32 v8, v6, 16, 1
	v_add3_u32 v6, v6, v8, s82
	ds_write_b16_d16_hi v69, v6 offset:4760
	v_mul_f32_e32 v6, v42, v71
	v_bfe_u32 v8, v6, 16, 1
	v_add3_u32 v6, v6, v8, s82
	ds_write_b16_d16_hi v69, v6 offset:13464
	v_mul_f32_e32 v6, v43, v70
	v_bfe_u32 v8, v6, 16, 1
	v_add3_u32 v6, v6, v8, s82
	ds_write_b16_d16_hi v69, v6 offset:4896
	v_mul_f32_e32 v6, v43, v71
	v_bfe_u32 v8, v6, 16, 1
	v_add3_u32 v6, v6, v8, s82
	ds_write_b16_d16_hi v69, v6 offset:13600
	v_mul_f32_e32 v6, v44, v70
	v_bfe_u32 v8, v6, 16, 1
	v_add3_u32 v6, v6, v8, s82
	ds_write_b16_d16_hi v69, v6 offset:5032
	v_mul_f32_e32 v6, v44, v71
	v_bfe_u32 v8, v6, 16, 1
	v_add3_u32 v6, v6, v8, s82
	ds_write_b16_d16_hi v69, v6 offset:13736
	v_mul_f32_e32 v6, v45, v70
	v_bfe_u32 v8, v6, 16, 1
	v_add3_u32 v6, v6, v8, s82
	ds_write_b16_d16_hi v69, v6 offset:5168
	v_mul_f32_e32 v6, v45, v71
	v_bfe_u32 v8, v6, 16, 1
	v_add3_u32 v6, v6, v8, s82
	ds_write_b16_d16_hi v69, v6 offset:13872
	v_mul_f32_e32 v6, v46, v70
	v_bfe_u32 v8, v6, 16, 1
	v_add3_u32 v6, v6, v8, s82
	ds_write_b16_d16_hi v69, v6 offset:5304
	v_mul_f32_e32 v6, v46, v71
	v_bfe_u32 v8, v6, 16, 1
	v_add3_u32 v6, v6, v8, s82
	ds_write_b16_d16_hi v69, v6 offset:14008
	v_mul_f32_e32 v6, v47, v70
	v_bfe_u32 v8, v6, 16, 1
	v_add3_u32 v6, v6, v8, s82
	ds_write_b16_d16_hi v69, v6 offset:5440
	v_mul_f32_e32 v6, v47, v71
	v_bfe_u32 v8, v6, 16, 1
	v_add3_u32 v6, v6, v8, s82
	ds_write_b16_d16_hi v69, v6 offset:14144
	v_mul_f32_e32 v6, v48, v70
	v_bfe_u32 v8, v6, 16, 1
	v_add3_u32 v6, v6, v8, s82
	ds_write_b16_d16_hi v69, v6 offset:5576
	v_mul_f32_e32 v6, v48, v71
	v_bfe_u32 v8, v6, 16, 1
	v_add3_u32 v6, v6, v8, s82
	ds_write_b16_d16_hi v69, v6 offset:14280
	v_mul_f32_e32 v6, v49, v70
	v_bfe_u32 v8, v6, 16, 1
	v_add3_u32 v6, v6, v8, s82
	ds_write_b16_d16_hi v69, v6 offset:5712
	v_mul_f32_e32 v6, v49, v71
	v_bfe_u32 v8, v6, 16, 1
	v_add3_u32 v6, v6, v8, s82
	ds_write_b16_d16_hi v69, v6 offset:14416
	v_mul_f32_e32 v6, v50, v70
	v_bfe_u32 v8, v6, 16, 1
	v_add3_u32 v6, v6, v8, s82
	ds_write_b16_d16_hi v69, v6 offset:5848
	v_mul_f32_e32 v6, v50, v71
	v_bfe_u32 v8, v6, 16, 1
	v_add3_u32 v6, v6, v8, s82
	ds_write_b16_d16_hi v69, v6 offset:14552
	v_mul_f32_e32 v6, v51, v70
	v_bfe_u32 v8, v6, 16, 1
	v_add3_u32 v6, v6, v8, s82
	ds_write_b16_d16_hi v69, v6 offset:5984
	v_mul_f32_e32 v6, v51, v71
	v_bfe_u32 v8, v6, 16, 1
	v_add3_u32 v6, v6, v8, s82
	ds_write_b16_d16_hi v69, v6 offset:14688
	v_mul_f32_e32 v6, v52, v70
	v_bfe_u32 v8, v6, 16, 1
	v_add3_u32 v6, v6, v8, s82
	ds_write_b16_d16_hi v69, v6 offset:6120
	v_mul_f32_e32 v6, v52, v71
	v_bfe_u32 v8, v6, 16, 1
	v_add3_u32 v6, v6, v8, s82
	ds_write_b16_d16_hi v69, v6 offset:14824
	v_mul_f32_e32 v6, v53, v70
	v_bfe_u32 v8, v6, 16, 1
	v_add3_u32 v6, v6, v8, s82
	ds_write_b16_d16_hi v69, v6 offset:6256
	v_mul_f32_e32 v6, v53, v71
	v_bfe_u32 v8, v6, 16, 1
	v_add3_u32 v6, v6, v8, s82
	ds_write_b16_d16_hi v69, v6 offset:14960
	v_mul_f32_e32 v6, v54, v70
	v_bfe_u32 v8, v6, 16, 1
	v_add3_u32 v6, v6, v8, s82
	ds_write_b16_d16_hi v69, v6 offset:6392
	v_mul_f32_e32 v6, v54, v71
	v_bfe_u32 v8, v6, 16, 1
	v_add3_u32 v6, v6, v8, s82
	ds_write_b16_d16_hi v69, v6 offset:15096
	v_mul_f32_e32 v6, v55, v70
	v_bfe_u32 v8, v6, 16, 1
	v_add3_u32 v6, v6, v8, s82
	ds_write_b16_d16_hi v69, v6 offset:6528
	v_mul_f32_e32 v6, v55, v71
	v_bfe_u32 v8, v6, 16, 1
	v_add3_u32 v6, v6, v8, s82
	ds_write_b16_d16_hi v69, v6 offset:15232
	v_mul_f32_e32 v6, v11, v70
	v_bfe_u32 v8, v6, 16, 1
	v_add3_u32 v6, v6, v8, s82
	ds_write_b16_d16_hi v69, v6 offset:6664
	v_mul_f32_e32 v6, v11, v71
	v_bfe_u32 v8, v6, 16, 1
	v_add3_u32 v6, v6, v8, s82
	ds_write_b16_d16_hi v69, v6 offset:15368
	v_mul_f32_e32 v6, v56, v70
	v_bfe_u32 v8, v6, 16, 1
	v_add3_u32 v6, v6, v8, s82
	ds_write_b16_d16_hi v69, v6 offset:6800
	v_mul_f32_e32 v6, v56, v71
	v_bfe_u32 v8, v6, 16, 1
	v_add3_u32 v6, v6, v8, s82
	ds_write_b16_d16_hi v69, v6 offset:15504
	v_mul_f32_e32 v6, v57, v70
	v_bfe_u32 v8, v6, 16, 1
	v_add3_u32 v6, v6, v8, s82
	ds_write_b16_d16_hi v69, v6 offset:6936
	v_mul_f32_e32 v6, v57, v71
	v_bfe_u32 v8, v6, 16, 1
	v_add3_u32 v6, v6, v8, s82
	ds_write_b16_d16_hi v69, v6 offset:15640
	v_mul_f32_e32 v6, v58, v70
	v_bfe_u32 v8, v6, 16, 1
	v_add3_u32 v6, v6, v8, s82
	ds_write_b16_d16_hi v69, v6 offset:7072
	v_mul_f32_e32 v6, v58, v71
	v_bfe_u32 v8, v6, 16, 1
	v_add3_u32 v6, v6, v8, s82
	ds_write_b16_d16_hi v69, v6 offset:15776
	v_mul_f32_e32 v6, v59, v70
	v_bfe_u32 v8, v6, 16, 1
	v_add3_u32 v6, v6, v8, s82
	ds_write_b16_d16_hi v69, v6 offset:7208
	v_mul_f32_e32 v6, v59, v71
	v_bfe_u32 v8, v6, 16, 1
	v_add3_u32 v6, v6, v8, s82
	ds_write_b16_d16_hi v69, v6 offset:15912
	v_mul_f32_e32 v6, v60, v70
	v_bfe_u32 v8, v6, 16, 1
	v_add3_u32 v6, v6, v8, s82
	ds_write_b16_d16_hi v69, v6 offset:7344
	v_mul_f32_e32 v6, v60, v71
	v_bfe_u32 v8, v6, 16, 1
	v_add3_u32 v6, v6, v8, s82
	ds_write_b16_d16_hi v69, v6 offset:16048
	v_mul_f32_e32 v6, v61, v70
	v_bfe_u32 v8, v6, 16, 1
	v_add3_u32 v6, v6, v8, s82
	ds_write_b16_d16_hi v69, v6 offset:7480
	v_mul_f32_e32 v6, v61, v71
	v_bfe_u32 v8, v6, 16, 1
	v_add3_u32 v6, v6, v8, s82
	ds_write_b16_d16_hi v69, v6 offset:16184
	v_mul_f32_e32 v6, v62, v70
	v_bfe_u32 v8, v6, 16, 1
	v_add3_u32 v6, v6, v8, s82
	ds_write_b16_d16_hi v69, v6 offset:7616
	v_mul_f32_e32 v6, v62, v71
	v_bfe_u32 v8, v6, 16, 1
	v_add3_u32 v6, v6, v8, s82
	ds_write_b16_d16_hi v69, v6 offset:16320
	v_mul_f32_e32 v6, v63, v70
	v_bfe_u32 v8, v6, 16, 1
	v_add3_u32 v6, v6, v8, s82
	ds_write_b16_d16_hi v69, v6 offset:7752
	v_mul_f32_e32 v6, v63, v71
	v_bfe_u32 v8, v6, 16, 1
	v_add3_u32 v6, v6, v8, s82
	ds_write_b16_d16_hi v69, v6 offset:16456
	v_mul_f32_e32 v6, v64, v70
	v_bfe_u32 v8, v6, 16, 1
	v_add3_u32 v6, v6, v8, s82
	ds_write_b16_d16_hi v69, v6 offset:7888
	v_mul_f32_e32 v6, v64, v71
	v_bfe_u32 v8, v6, 16, 1
	v_add3_u32 v6, v6, v8, s82
	ds_write_b16_d16_hi v69, v6 offset:16592
	v_mul_f32_e32 v6, v65, v70
	v_bfe_u32 v8, v6, 16, 1
	v_add3_u32 v6, v6, v8, s82
	ds_write_b16_d16_hi v69, v6 offset:8024
	v_mul_f32_e32 v6, v65, v71
	v_bfe_u32 v8, v6, 16, 1
	v_add3_u32 v6, v6, v8, s82
	ds_write_b16_d16_hi v69, v6 offset:16728
	v_mul_f32_e32 v6, v66, v70
	v_bfe_u32 v8, v6, 16, 1
	v_add3_u32 v6, v6, v8, s82
	ds_write_b16_d16_hi v69, v6 offset:8160
	v_mul_f32_e32 v6, v66, v71
	v_bfe_u32 v8, v6, 16, 1
	v_add3_u32 v6, v6, v8, s82
	ds_write_b16_d16_hi v69, v6 offset:16864
	v_mul_f32_e32 v6, v67, v70
	v_bfe_u32 v8, v6, 16, 1
	v_add3_u32 v6, v6, v8, s82
	ds_write_b16_d16_hi v69, v6 offset:8296
	v_mul_f32_e32 v6, v67, v71
	v_bfe_u32 v8, v6, 16, 1
	v_add3_u32 v6, v6, v8, s82
	ds_write_b16_d16_hi v69, v6 offset:17000
	v_mul_f32_e32 v6, v7, v70
	v_bfe_u32 v8, v6, 16, 1
	v_add3_u32 v6, v6, v8, s82
	ds_write_b16_d16_hi v69, v6 offset:8432
	v_mul_f32_e32 v6, v7, v71
	v_bfe_u32 v7, v6, 16, 1
	v_add3_u32 v6, v6, v7, s82
	ds_write_b16_d16_hi v69, v6 offset:17136
	v_mul_f32_e32 v6, v68, v70
	v_bfe_u32 v7, v6, 16, 1
	v_add3_u32 v6, v6, v7, s82
	ds_write_b16_d16_hi v69, v6 offset:8568
	v_mul_f32_e32 v6, v68, v71
	v_bfe_u32 v7, v6, 16, 1
	v_add3_u32 v6, v6, v7, s82
	ds_write_b16_d16_hi v69, v6 offset:17272
	s_setprio 0
	s_branch .LBB0_498
